# MFMA order only: in the GIN, UP, GOUT and F1 K-loops the two K-halves of each accumulator issue back to back (pure permutation of independent MFMAs)
# speedup vs baseline: 1.0079x; 1.0039x over previous
; #define PG8_STAGE(bufoff, gbase, voff) do { _Pragma("unroll") for (int _i = 0; _i < 2; ++_i) \
;         __builtin_amdgcn_global_load_lds((const unsigned*)((const char*)(gbase) + (voff)[_i]), (PG8_LAS unsigned*)(lds + (bufoff) + ldsw + _i * 8192), 16, 0, 0); } while (0)
; #define PG8_LDA(dst, b, h) do { _Pragma("unroll") for (int m = 0; m < 4; ++m) _Pragma("unroll") for (int k = 0; k < 2; ++k) dst[m][k] = *(const PG8_LAS bf16x8*)(lds + PG8_SA(b, h) + aoff + m * 2048 + k * 1024); } while (0)
; #define PG8_LDB(dst, b, h) do { _Pragma("unroll") for (int n = 0; n < 2; ++n) _Pragma("unroll") for (int k = 0; k < 2; ++k) dst[n][k] = *(const PG8_LAS bf16x8*)(lds + PG8_SB(b, h) + boff + n * 2048 + k * 1024); } while (0)
; #define PG8_MMA(ai, bj, At, Bt) do { __builtin_amdgcn_s_setprio(1); _Pragma("unroll") for (int m = 0; m < 4; ++m) _Pragma("unroll") for (int n = 0; n < 2; ++n) _Pragma("unroll") for (int k = 0; k < 2; ++k) \
;         acc[ai][bj][m][n] = __builtin_amdgcn_mfma_f32_16x16x32_bf16(Bt[n][k], At[m][k], acc[ai][bj][m][n], 0, 0, 0); __builtin_amdgcn_s_setprio(0); } while (0)
; #define PG8_WAIT_V(n) asm volatile("s_waitcnt vmcnt(" #n ")" ::: "memory")
; #define PG8_WAIT_L(n) asm volatile("s_waitcnt lgkmcnt(" #n ")" ::: "memory")
; template <class Epi, class Sched, bool ALIGN_EPI = true, bool SP2 = true>
; __device__ __forceinline__ void gemm_phase(PG8_LAS unsigned char* lds, const Gemm g, const Sched& S, const Epi& E, const int tid) {
;     ...
;             const bool last = (t == nt - 2);
;             const char* a1 = cA + (size_t)(t + 1) * kstep;
;             const char* a2 = last ? nA : cA + (size_t)(t + 2) * kstep; const char* b2 = last ? nB : cB + (size_t)(t + 2) * kstep;
;             const char* a3 = a2 + kstep; const char* b3 = b2 + kstep;
;             if (last && has_next) S.a_ready(nxt);
;             if constexpr (SP2) {
;             PG8_LDB(B0, 0, 0); PG8_LDB(B1, 0, 1); PG8_SCHED; PG8_LDA(At, 0, 0); PG8_STAGE(PG8_SA(1, 1), a1 + hstepA, voffA);
;             PG8_WAIT_V(8); PG8_WAIT_L(0); PG8_BAR; PG8_MMA(0, 0, At, B0); PG8_MMA(0, 1, At, B1); PG8_BAR; PG8_SCHED;
;             PG8_LDA(At, 0, 1); PG8_STAGE(PG8_SB(0, 0), b2, voffB); PG8_STAGE(PG8_SB(0, 1), b2 + hstepB, voffB); PG8_STAGE(PG8_SA(0, 0), a2, voffA);
;             PG8_WAIT_V(8); PG8_WAIT_L(0); PG8_BAR; PG8_MMA(1, 0, At, B0); PG8_MMA(1, 1, At, B1); PG8_BAR; PG8_SCHED;
.LBB0_381:
	s_add_u32 s25, s62, 0xfff80080
	s_addc_u32 s26, s63, -1
	s_add_i32 s27, 0, 0x10000
	s_cmp_eq_u32 s24, 28
	s_cselect_b32 s69, s18, s26
	s_cselect_b32 s68, s19, s25
	s_cselect_b32 s67, s20, s23
	s_cselect_b32 s66, s21, s22
	s_add_i32 s25, 0, 0x14000
	v_add_u32_e32 v158, s27, v163
	v_add_u32_e32 v165, s25, v163
	ds_read_b128 v[146:149], v158
	ds_read_b128 v[150:153], v158 offset:1024
	ds_read_b128 v[154:157], v158 offset:2048
	ds_read_b128 v[158:161], v158 offset:3072
	ds_read_b128 v[166:169], v165
	ds_read_b128 v[170:173], v165 offset:1024
	ds_read_b128 v[174:177], v165 offset:2048
	ds_read_b128 v[178:181], v165 offset:3072
	v_lshl_add_u64 v[200:201], s[62:63], 0, v[142:143]
	s_add_i32 m0, s82, 0xc000
	ds_read_b128 v[182:185], v164
	ds_read_b128 v[186:189], v164 offset:1024
	ds_read_b128 v[190:193], v164 offset:2048
	ds_read_b128 v[194:197], v164 offset:3072
	ds_read_b128 v[206:209], v164 offset:4096
	ds_read_b128 v[210:213], v164 offset:5120
	ds_read_b128 v[222:225], v164 offset:6144
	ds_read_b128 v[226:229], v164 offset:7168
	global_load_lds_dwordx4 v[200:201], off
	v_lshl_add_u64 v[200:201], s[62:63], 0, v[144:145]
	s_add_i32 m0, s82, 0xe000
	s_nop 0
	global_load_lds_dwordx4 v[200:201], off
	s_waitcnt vmcnt(8)
	s_waitcnt lgkmcnt(0)
	s_barrier
	s_setprio 1
	s_waitcnt lgkmcnt(0)
	v_mfma_f32_16x16x32_bf16 v[126:129], v[146:149], v[182:185], v[126:129]
	v_mfma_f32_16x16x32_bf16 v[126:129], v[150:153], v[186:189], v[126:129]
	v_mfma_f32_16x16x32_bf16 v[122:125], v[154:157], v[182:185], v[122:125]
	v_mfma_f32_16x16x32_bf16 v[122:125], v[158:161], v[186:189], v[122:125]
	v_mfma_f32_16x16x32_bf16 v[110:113], v[146:149], v[190:193], v[110:113]
	v_mfma_f32_16x16x32_bf16 v[110:113], v[150:153], v[194:197], v[110:113]
	v_mfma_f32_16x16x32_bf16 v[106:109], v[154:157], v[190:193], v[106:109]
	v_mfma_f32_16x16x32_bf16 v[106:109], v[158:161], v[194:197], v[106:109]
	v_mfma_f32_16x16x32_bf16 v[92:95], v[146:149], v[206:209], v[92:95]
	v_mfma_f32_16x16x32_bf16 v[92:95], v[150:153], v[210:213], v[92:95]
	v_mfma_f32_16x16x32_bf16 v[88:91], v[154:157], v[206:209], v[88:91]
	v_mfma_f32_16x16x32_bf16 v[88:91], v[158:161], v[210:213], v[88:91]
	v_mfma_f32_16x16x32_bf16 v[76:79], v[146:149], v[222:225], v[76:79]
	v_mfma_f32_16x16x32_bf16 v[76:79], v[150:153], v[226:229], v[76:79]
	v_mfma_f32_16x16x32_bf16 v[72:75], v[154:157], v[222:225], v[72:75]
	v_mfma_f32_16x16x32_bf16 v[72:75], v[158:161], v[226:229], v[72:75]
	s_setprio 0
	s_setprio 1
	v_mfma_f32_16x16x32_bf16 v[118:121], v[166:169], v[182:185], v[118:121]
	v_mfma_f32_16x16x32_bf16 v[118:121], v[170:173], v[186:189], v[118:121]
	v_mfma_f32_16x16x32_bf16 v[114:117], v[174:177], v[182:185], v[114:117]
	v_mfma_f32_16x16x32_bf16 v[114:117], v[178:181], v[186:189], v[114:117]
	v_mfma_f32_16x16x32_bf16 v[102:105], v[166:169], v[190:193], v[102:105]
	v_mfma_f32_16x16x32_bf16 v[102:105], v[170:173], v[194:197], v[102:105]
	v_mfma_f32_16x16x32_bf16 v[98:101], v[174:177], v[190:193], v[98:101]
	v_mfma_f32_16x16x32_bf16 v[98:101], v[178:181], v[194:197], v[98:101]
	v_mfma_f32_16x16x32_bf16 v[84:87], v[166:169], v[206:209], v[84:87]
	v_mfma_f32_16x16x32_bf16 v[84:87], v[170:173], v[210:213], v[84:87]
	v_mfma_f32_16x16x32_bf16 v[80:83], v[174:177], v[206:209], v[80:83]
	v_mfma_f32_16x16x32_bf16 v[80:83], v[178:181], v[210:213], v[80:83]
	v_mfma_f32_16x16x32_bf16 v[68:71], v[166:169], v[222:225], v[68:71]
	v_mfma_f32_16x16x32_bf16 v[68:71], v[170:173], v[226:229], v[68:71]
	v_mfma_f32_16x16x32_bf16 v[64:67], v[174:177], v[222:225], v[64:67]
	v_mfma_f32_16x16x32_bf16 v[64:67], v[178:181], v[226:229], v[64:67]
	s_setprio 0
	s_barrier
	s_add_i32 s26, s27, s73
	v_lshl_add_u64 v[200:201], s[66:67], 0, v[132:133]
	s_mov_b32 m0, s26
	ds_read_b128 v[182:185], v164 offset:16384
	ds_read_b128 v[186:189], v164 offset:17408
	ds_read_b128 v[190:193], v164 offset:18432
	ds_read_b128 v[194:197], v164 offset:19456
	ds_read_b128 v[206:209], v164 offset:20480
	ds_read_b128 v[210:213], v164 offset:21504
	ds_read_b128 v[222:225], v164 offset:22528
	ds_read_b128 v[226:229], v164 offset:23552
	global_load_lds_dwordx4 v[200:201], off
	s_add_i32 m0, s26, 0x2000
	s_add_u32 s26, s66, 0x80000
	v_lshl_add_u64 v[202:203], s[66:67], 0, v[136:137]
	s_addc_u32 s27, s67, 0
	s_add_i32 s25, s25, s73
	global_load_lds_dwordx4 v[202:203], off
	v_lshl_add_u64 v[230:231], s[26:27], 0, v[132:133]
	s_mov_b32 m0, s25
	v_lshl_add_u64 v[232:233], s[68:69], 0, v[134:135]
	global_load_lds_dwordx4 v[230:231], off
	v_lshl_add_u64 v[230:231], s[26:27], 0, v[136:137]
	s_add_i32 m0, s25, 0x2000
	s_nop 0
	global_load_lds_dwordx4 v[230:231], off
	v_lshl_add_u64 v[230:231], s[68:69], 0, v[130:131]
	s_mov_b32 m0, s82
	s_nop 0
	global_load_lds_dwordx4 v[230:231], off
	s_mov_b32 m0, s83
	s_nop 0
	global_load_lds_dwordx4 v[232:233], off
	s_waitcnt vmcnt(8)
	s_waitcnt lgkmcnt(0)
	s_barrier
; #define PG8_STAGE(bufoff, gbase, voff) do { _Pragma("unroll") for (int _i = 0; _i < 2; ++_i) \
;         __builtin_amdgcn_global_load_lds((const unsigned*)((const char*)(gbase) + (voff)[_i]), (PG8_LAS unsigned*)(lds + (bufoff) + ldsw + _i * 8192), 16, 0, 0); } while (0)
; #define PG8_LDA(dst, b, h) do { _Pragma("unroll") for (int m = 0; m < 4; ++m) _Pragma("unroll") for (int k = 0; k < 2; ++k) dst[m][k] = *(const PG8_LAS bf16x8*)(lds + PG8_SA(b, h) + aoff + m * 2048 + k * 1024); } while (0)
; #define PG8_LDB(dst, b, h) do { _Pragma("unroll") for (int n = 0; n < 2; ++n) _Pragma("unroll") for (int k = 0; k < 2; ++k) dst[n][k] = *(const PG8_LAS bf16x8*)(lds + PG8_SB(b, h) + boff + n * 2048 + k * 1024); } while (0)
; #define PG8_MMA(ai, bj, At, Bt) do { __builtin_amdgcn_s_setprio(1); _Pragma("unroll") for (int m = 0; m < 4; ++m) _Pragma("unroll") for (int n = 0; n < 2; ++n) _Pragma("unroll") for (int k = 0; k < 2; ++k) \
;         acc[ai][bj][m][n] = __builtin_amdgcn_mfma_f32_16x16x32_bf16(Bt[n][k], At[m][k], acc[ai][bj][m][n], 0, 0, 0); __builtin_amdgcn_s_setprio(0); } while (0)
; #define PG8_WAIT_V(n) asm volatile("s_waitcnt vmcnt(" #n ")" ::: "memory")
; #define PG8_WAIT_L(n) asm volatile("s_waitcnt lgkmcnt(" #n ")" ::: "memory")
; #define PG8_BAR __builtin_amdgcn_s_barrier()
; #define PG8_SCHED __builtin_amdgcn_sched_barrier(0)
; template <class Epi, class Sched, bool ALIGN_EPI = true, bool SP2 = true>
; __device__ __forceinline__ void gemm_phase(PG8_LAS unsigned char* lds, const Gemm g, const Sched& S, const Epi& E, const int tid) {
;     ...
;             PG8_WAIT_V(8); PG8_WAIT_L(0); PG8_BAR; PG8_MMA(1, 0, At, B0); PG8_MMA(1, 1, At, B1); PG8_BAR; PG8_SCHED;
;             PG8_LDB(B0, 1, 0); PG8_LDB(B1, 1, 1); PG8_SCHED; PG8_LDA(At, 1, 0); PG8_STAGE(PG8_SA(0, 1), a2 + hstepA, voffA);
;             PG8_WAIT_V(8); PG8_WAIT_L(0); PG8_BAR; PG8_MMA(0, 0, At, B0); PG8_MMA(0, 1, At, B1); PG8_BAR; PG8_SCHED;
	s_setprio 1
	s_waitcnt lgkmcnt(0)
	v_mfma_f32_16x16x32_bf16 v[60:63], v[146:149], v[182:185], v[60:63]
	v_mfma_f32_16x16x32_bf16 v[60:63], v[150:153], v[186:189], v[60:63]
	v_mfma_f32_16x16x32_bf16 v[56:59], v[154:157], v[182:185], v[56:59]
	v_mfma_f32_16x16x32_bf16 v[56:59], v[158:161], v[186:189], v[56:59]
	v_mfma_f32_16x16x32_bf16 v[44:47], v[146:149], v[190:193], v[44:47]
	v_mfma_f32_16x16x32_bf16 v[44:47], v[150:153], v[194:197], v[44:47]
	v_mfma_f32_16x16x32_bf16 v[40:43], v[154:157], v[190:193], v[40:43]
	v_mfma_f32_16x16x32_bf16 v[40:43], v[158:161], v[194:197], v[40:43]
	v_mfma_f32_16x16x32_bf16 v[28:31], v[146:149], v[206:209], v[28:31]
	v_mfma_f32_16x16x32_bf16 v[28:31], v[150:153], v[210:213], v[28:31]
	v_mfma_f32_16x16x32_bf16 v[24:27], v[154:157], v[206:209], v[24:27]
	v_mfma_f32_16x16x32_bf16 v[24:27], v[158:161], v[210:213], v[24:27]
	v_mfma_f32_16x16x32_bf16 v[12:15], v[146:149], v[222:225], v[12:15]
	v_mfma_f32_16x16x32_bf16 v[12:15], v[150:153], v[226:229], v[12:15]
	v_mfma_f32_16x16x32_bf16 v[8:11], v[154:157], v[222:225], v[8:11]
	v_mfma_f32_16x16x32_bf16 v[8:11], v[158:161], v[226:229], v[8:11]
	s_setprio 0
	s_setprio 1
	v_mfma_f32_16x16x32_bf16 v[52:55], v[166:169], v[182:185], v[52:55]
	v_mfma_f32_16x16x32_bf16 v[52:55], v[170:173], v[186:189], v[52:55]
	v_mfma_f32_16x16x32_bf16 v[48:51], v[174:177], v[182:185], v[48:51]
	v_mfma_f32_16x16x32_bf16 v[48:51], v[178:181], v[186:189], v[48:51]
	v_mfma_f32_16x16x32_bf16 v[36:39], v[166:169], v[190:193], v[36:39]
	v_mfma_f32_16x16x32_bf16 v[36:39], v[170:173], v[194:197], v[36:39]
	v_mfma_f32_16x16x32_bf16 v[32:35], v[174:177], v[190:193], v[32:35]
	v_mfma_f32_16x16x32_bf16 v[32:35], v[178:181], v[194:197], v[32:35]
	v_mfma_f32_16x16x32_bf16 v[20:23], v[166:169], v[206:209], v[20:23]
	v_mfma_f32_16x16x32_bf16 v[20:23], v[170:173], v[210:213], v[20:23]
	v_mfma_f32_16x16x32_bf16 v[16:19], v[174:177], v[206:209], v[16:19]
	v_mfma_f32_16x16x32_bf16 v[16:19], v[178:181], v[210:213], v[16:19]
	v_mfma_f32_16x16x32_bf16 v[4:7], v[166:169], v[222:225], v[4:7]
	v_mfma_f32_16x16x32_bf16 v[4:7], v[170:173], v[226:229], v[4:7]
	v_mfma_f32_16x16x32_bf16 v[0:3], v[174:177], v[222:225], v[0:3]
	v_mfma_f32_16x16x32_bf16 v[0:3], v[178:181], v[226:229], v[0:3]
	s_setprio 0
	s_barrier
	s_add_i32 s25, 0, 0x18000
	s_add_i32 s28, 0, 0x1c000
	v_add_u32_e32 v158, s25, v163
	v_add_u32_e32 v165, s28, v163
	ds_read_b128 v[146:149], v158
	ds_read_b128 v[150:153], v158 offset:1024
	ds_read_b128 v[154:157], v158 offset:2048
	ds_read_b128 v[158:161], v158 offset:3072
	ds_read_b128 v[166:169], v165
	ds_read_b128 v[170:173], v165 offset:1024
	ds_read_b128 v[174:177], v165 offset:2048
	ds_read_b128 v[178:181], v165 offset:3072
	s_add_u32 s26, s68, 0x80000
	s_addc_u32 s27, s69, 0
	s_mov_b32 m0, s84
	v_lshl_add_u64 v[234:235], s[26:27], 0, v[130:131]
	ds_read_b128 v[182:185], v164 offset:32768
	ds_read_b128 v[186:189], v164 offset:33792
	ds_read_b128 v[190:193], v164 offset:34816
	ds_read_b128 v[194:197], v164 offset:35840
	ds_read_b128 v[206:209], v164 offset:36864
	ds_read_b128 v[210:213], v164 offset:37888
	ds_read_b128 v[222:225], v164 offset:38912
	ds_read_b128 v[226:229], v164 offset:39936
	global_load_lds_dwordx4 v[234:235], off
	v_lshl_add_u64 v[234:235], s[26:27], 0, v[134:135]
	s_mov_b32 m0, s85
	s_nop 0
	global_load_lds_dwordx4 v[234:235], off
	s_waitcnt vmcnt(8)
	s_waitcnt lgkmcnt(0)
	s_barrier
	s_setprio 1
	s_waitcnt lgkmcnt(0)
	v_mfma_f32_16x16x32_bf16 v[126:129], v[146:149], v[182:185], v[126:129]
	v_mfma_f32_16x16x32_bf16 v[126:129], v[150:153], v[186:189], v[126:129]
	v_mfma_f32_16x16x32_bf16 v[122:125], v[154:157], v[182:185], v[122:125]
	v_mfma_f32_16x16x32_bf16 v[122:125], v[158:161], v[186:189], v[122:125]
	v_mfma_f32_16x16x32_bf16 v[110:113], v[146:149], v[190:193], v[110:113]
	v_mfma_f32_16x16x32_bf16 v[110:113], v[150:153], v[194:197], v[110:113]
	v_mfma_f32_16x16x32_bf16 v[106:109], v[154:157], v[190:193], v[106:109]
	v_mfma_f32_16x16x32_bf16 v[106:109], v[158:161], v[194:197], v[106:109]
	v_mfma_f32_16x16x32_bf16 v[92:95], v[146:149], v[206:209], v[92:95]
	v_mfma_f32_16x16x32_bf16 v[92:95], v[150:153], v[210:213], v[92:95]
	v_mfma_f32_16x16x32_bf16 v[88:91], v[154:157], v[206:209], v[88:91]
	v_mfma_f32_16x16x32_bf16 v[88:91], v[158:161], v[210:213], v[88:91]
	v_mfma_f32_16x16x32_bf16 v[76:79], v[146:149], v[222:225], v[76:79]
	v_mfma_f32_16x16x32_bf16 v[76:79], v[150:153], v[226:229], v[76:79]
	v_mfma_f32_16x16x32_bf16 v[72:75], v[154:157], v[222:225], v[72:75]
	v_mfma_f32_16x16x32_bf16 v[72:75], v[158:161], v[226:229], v[72:75]
	s_setprio 0
	s_setprio 1
	v_mfma_f32_16x16x32_bf16 v[118:121], v[166:169], v[182:185], v[118:121]
	v_mfma_f32_16x16x32_bf16 v[118:121], v[170:173], v[186:189], v[118:121]
	v_mfma_f32_16x16x32_bf16 v[114:117], v[174:177], v[182:185], v[114:117]
	v_mfma_f32_16x16x32_bf16 v[114:117], v[178:181], v[186:189], v[114:117]
	v_mfma_f32_16x16x32_bf16 v[102:105], v[166:169], v[190:193], v[102:105]
	v_mfma_f32_16x16x32_bf16 v[102:105], v[170:173], v[194:197], v[102:105]
	v_mfma_f32_16x16x32_bf16 v[98:101], v[174:177], v[190:193], v[98:101]
	v_mfma_f32_16x16x32_bf16 v[98:101], v[178:181], v[194:197], v[98:101]
	v_mfma_f32_16x16x32_bf16 v[84:87], v[166:169], v[206:209], v[84:87]
	v_mfma_f32_16x16x32_bf16 v[84:87], v[170:173], v[210:213], v[84:87]
	v_mfma_f32_16x16x32_bf16 v[80:83], v[174:177], v[206:209], v[80:83]
	v_mfma_f32_16x16x32_bf16 v[80:83], v[178:181], v[210:213], v[80:83]
	v_mfma_f32_16x16x32_bf16 v[68:71], v[166:169], v[222:225], v[68:71]
	v_mfma_f32_16x16x32_bf16 v[68:71], v[170:173], v[226:229], v[68:71]
	v_mfma_f32_16x16x32_bf16 v[64:67], v[174:177], v[222:225], v[64:67]
	v_mfma_f32_16x16x32_bf16 v[64:67], v[178:181], v[226:229], v[64:67]
	s_setprio 0
	s_barrier
; #define PG8_STAGE(bufoff, gbase, voff) do { _Pragma("unroll") for (int _i = 0; _i < 2; ++_i) \
;         __builtin_amdgcn_global_load_lds((const unsigned*)((const char*)(gbase) + (voff)[_i]), (PG8_LAS unsigned*)(lds + (bufoff) + ldsw + _i * 8192), 16, 0, 0); } while (0)
; #define PG8_LDA(dst, b, h) do { _Pragma("unroll") for (int m = 0; m < 4; ++m) _Pragma("unroll") for (int k = 0; k < 2; ++k) dst[m][k] = *(const PG8_LAS bf16x8*)(lds + PG8_SA(b, h) + aoff + m * 2048 + k * 1024); } while (0)
; #define PG8_MMA(ai, bj, At, Bt) do { __builtin_amdgcn_s_setprio(1); _Pragma("unroll") for (int m = 0; m < 4; ++m) _Pragma("unroll") for (int n = 0; n < 2; ++n) _Pragma("unroll") for (int k = 0; k < 2; ++k) \
;         acc[ai][bj][m][n] = __builtin_amdgcn_mfma_f32_16x16x32_bf16(Bt[n][k], At[m][k], acc[ai][bj][m][n], 0, 0, 0); __builtin_amdgcn_s_setprio(0); } while (0)
; #define PG8_WAIT_V(n) asm volatile("s_waitcnt vmcnt(" #n ")" ::: "memory")
; #define PG8_WAIT_L(n) asm volatile("s_waitcnt lgkmcnt(" #n ")" ::: "memory")
; #define PG8_BAR __builtin_amdgcn_s_barrier()
; #define PG8_SCHED __builtin_amdgcn_sched_barrier(0)
; template <class Epi, class Sched, bool ALIGN_EPI = true, bool SP2 = true>
; __device__ __forceinline__ void gemm_phase(PG8_LAS unsigned char* lds, const Gemm g, const Sched& S, const Epi& E, const int tid) {
;     ...
;         for (int t = 0; t < nt; t += 2) {
;             const bool last = (t == nt - 2);
;             const char* a1 = cA + (size_t)(t + 1) * kstep;
;             const char* a2 = last ? nA : cA + (size_t)(t + 2) * kstep; const char* b2 = last ? nB : cB + (size_t)(t + 2) * kstep;
;             const char* a3 = a2 + kstep; const char* b3 = b2 + kstep;
;     ...
;             PG8_LDA(At, 1, 1); PG8_STAGE(PG8_SB(1, 0), b3, voffB); PG8_STAGE(PG8_SB(1, 1), b3 + hstepB, voffB); PG8_STAGE(PG8_SA(1, 0), a3, voffA);
;             PG8_WAIT_V(8); PG8_WAIT_L(0); PG8_BAR; PG8_MMA(1, 0, At, B0); PG8_MMA(1, 1, At, B1); PG8_BAR; PG8_SCHED;
	s_add_i32 s25, s25, s73
	v_lshl_add_u64 v[200:201], v[200:201], 0, s[4:5]
	s_mov_b32 m0, s25
	ds_read_b128 v[182:185], v164 offset:49152
	ds_read_b128 v[186:189], v164 offset:50176
	ds_read_b128 v[190:193], v164 offset:51200
	ds_read_b128 v[194:197], v164 offset:52224
	ds_read_b128 v[206:209], v164 offset:53248
	ds_read_b128 v[210:213], v164 offset:54272
	ds_read_b128 v[222:225], v164 offset:55296
	ds_read_b128 v[226:229], v164 offset:56320
	global_load_lds_dwordx4 v[200:201], off
	s_add_i32 m0, s25, 0x2000
	s_add_u32 s26, s66, 0x80080
	v_lshl_add_u64 v[200:201], v[202:203], 0, s[4:5]
	s_addc_u32 s27, s67, 0
	s_add_i32 s25, s28, s73
	global_load_lds_dwordx4 v[200:201], off
	v_lshl_add_u64 v[200:201], s[26:27], 0, v[132:133]
	s_mov_b32 m0, s25
	s_nop 0
	global_load_lds_dwordx4 v[200:201], off
	v_lshl_add_u64 v[200:201], s[26:27], 0, v[136:137]
	s_add_i32 m0, s25, 0x2000
	s_nop 0
	global_load_lds_dwordx4 v[200:201], off
	v_lshl_add_u64 v[200:201], v[230:231], 0, s[4:5]
	s_mov_b32 m0, s88
	s_nop 0
	global_load_lds_dwordx4 v[200:201], off
	v_lshl_add_u64 v[200:201], v[232:233], 0, s[4:5]
	s_mov_b32 m0, s89
	s_nop 0
	global_load_lds_dwordx4 v[200:201], off
	s_waitcnt vmcnt(8)
	s_waitcnt lgkmcnt(0)
	s_barrier
	s_setprio 1
	s_waitcnt lgkmcnt(0)
	v_mfma_f32_16x16x32_bf16 v[60:63], v[146:149], v[182:185], v[60:63]
	v_mfma_f32_16x16x32_bf16 v[60:63], v[150:153], v[186:189], v[60:63]
	v_mfma_f32_16x16x32_bf16 v[56:59], v[154:157], v[182:185], v[56:59]
	v_mfma_f32_16x16x32_bf16 v[56:59], v[158:161], v[186:189], v[56:59]
	v_mfma_f32_16x16x32_bf16 v[44:47], v[146:149], v[190:193], v[44:47]
	v_mfma_f32_16x16x32_bf16 v[44:47], v[150:153], v[194:197], v[44:47]
	v_mfma_f32_16x16x32_bf16 v[40:43], v[154:157], v[190:193], v[40:43]
	v_mfma_f32_16x16x32_bf16 v[40:43], v[158:161], v[194:197], v[40:43]
	v_mfma_f32_16x16x32_bf16 v[28:31], v[146:149], v[206:209], v[28:31]
	v_mfma_f32_16x16x32_bf16 v[28:31], v[150:153], v[210:213], v[28:31]
	v_mfma_f32_16x16x32_bf16 v[24:27], v[154:157], v[206:209], v[24:27]
	v_mfma_f32_16x16x32_bf16 v[24:27], v[158:161], v[210:213], v[24:27]
	v_mfma_f32_16x16x32_bf16 v[12:15], v[146:149], v[222:225], v[12:15]
	v_mfma_f32_16x16x32_bf16 v[12:15], v[150:153], v[226:229], v[12:15]
	v_mfma_f32_16x16x32_bf16 v[8:11], v[154:157], v[222:225], v[8:11]
	v_mfma_f32_16x16x32_bf16 v[8:11], v[158:161], v[226:229], v[8:11]
	s_setprio 0
	s_setprio 1
	v_mfma_f32_16x16x32_bf16 v[52:55], v[166:169], v[182:185], v[52:55]
	v_mfma_f32_16x16x32_bf16 v[52:55], v[170:173], v[186:189], v[52:55]
	v_mfma_f32_16x16x32_bf16 v[48:51], v[174:177], v[182:185], v[48:51]
	v_mfma_f32_16x16x32_bf16 v[48:51], v[178:181], v[186:189], v[48:51]
	v_mfma_f32_16x16x32_bf16 v[36:39], v[166:169], v[190:193], v[36:39]
	v_mfma_f32_16x16x32_bf16 v[36:39], v[170:173], v[194:197], v[36:39]
	v_mfma_f32_16x16x32_bf16 v[32:35], v[174:177], v[190:193], v[32:35]
	v_mfma_f32_16x16x32_bf16 v[32:35], v[178:181], v[194:197], v[32:35]
	v_mfma_f32_16x16x32_bf16 v[20:23], v[166:169], v[206:209], v[20:23]
	v_mfma_f32_16x16x32_bf16 v[20:23], v[170:173], v[210:213], v[20:23]
	v_mfma_f32_16x16x32_bf16 v[16:19], v[174:177], v[206:209], v[16:19]
	v_mfma_f32_16x16x32_bf16 v[16:19], v[178:181], v[210:213], v[16:19]
	v_mfma_f32_16x16x32_bf16 v[4:7], v[166:169], v[222:225], v[4:7]
	v_mfma_f32_16x16x32_bf16 v[4:7], v[170:173], v[226:229], v[4:7]
	v_mfma_f32_16x16x32_bf16 v[0:3], v[174:177], v[222:225], v[0:3]
	v_mfma_f32_16x16x32_bf16 v[0:3], v[178:181], v[226:229], v[0:3]
	s_setprio 0
	s_barrier
	s_add_i32 s24, s24, 2
	s_add_u32 s62, s62, 0x100
	s_addc_u32 s63, s63, 0
	s_add_u32 s22, s22, 0x100
	s_addc_u32 s23, s23, 0
	s_cmp_gt_u32 s24, 29
	s_cbranch_scc0 .LBB0_381
	s_and_b64 vcc, exec, s[52:53]
	s_cbranch_vccz .LBB0_384
	s_barrier

; #define PG8_STAGE(bufoff, gbase, voff) do { _Pragma("unroll") for (int _i = 0; _i < 2; ++_i) \
;         __builtin_amdgcn_global_load_lds((const unsigned*)((const char*)(gbase) + (voff)[_i]), (PG8_LAS unsigned*)(lds + (bufoff) + ldsw + _i * 8192), 16, 0, 0); } while (0)
; #define PG8_LDA(dst, b, h) do { _Pragma("unroll") for (int m = 0; m < 4; ++m) _Pragma("unroll") for (int k = 0; k < 2; ++k) dst[m][k] = *(const PG8_LAS bf16x8*)(lds + PG8_SA(b, h) + aoff + m * 2048 + k * 1024); } while (0)
; #define PG8_LDB(dst, b, h) do { _Pragma("unroll") for (int n = 0; n < 2; ++n) _Pragma("unroll") for (int k = 0; k < 2; ++k) dst[n][k] = *(const PG8_LAS bf16x8*)(lds + PG8_SB(b, h) + boff + n * 2048 + k * 1024); } while (0)
; #define PG8_MMA(ai, bj, At, Bt) do { __builtin_amdgcn_s_setprio(1); _Pragma("unroll") for (int m = 0; m < 4; ++m) _Pragma("unroll") for (int n = 0; n < 2; ++n) _Pragma("unroll") for (int k = 0; k < 2; ++k) \
;         acc[ai][bj][m][n] = __builtin_amdgcn_mfma_f32_16x16x32_bf16(Bt[n][k], At[m][k], acc[ai][bj][m][n], 0, 0, 0); __builtin_amdgcn_s_setprio(0); } while (0)
; #define PG8_WAIT_V(n) asm volatile("s_waitcnt vmcnt(" #n ")" ::: "memory")
; #define PG8_WAIT_L(n) asm volatile("s_waitcnt lgkmcnt(" #n ")" ::: "memory")
; template <class Epi, class Sched, bool ALIGN_EPI = true, bool SP2 = true>
; __device__ __forceinline__ void gemm_phase(PG8_LAS unsigned char* lds, const Gemm g, const Sched& S, const Epi& E, const int tid) {
;     ...
;             const bool last = (t == nt - 2);
;             const char* a1 = cA + (size_t)(t + 1) * kstep;
;             const char* a2 = last ? nA : cA + (size_t)(t + 2) * kstep; const char* b2 = last ? nB : cB + (size_t)(t + 2) * kstep;
;             const char* a3 = a2 + kstep; const char* b3 = b2 + kstep;
;             if (last && has_next) S.a_ready(nxt);
;             if constexpr (SP2) {
;             PG8_LDB(B0, 0, 0); PG8_LDB(B1, 0, 1); PG8_SCHED; PG8_LDA(At, 0, 0); PG8_STAGE(PG8_SA(1, 1), a1 + hstepA, voffA);
;             PG8_WAIT_V(8); PG8_WAIT_L(0); PG8_BAR; PG8_MMA(0, 0, At, B0); PG8_MMA(0, 1, At, B1); PG8_BAR; PG8_SCHED;
;             PG8_LDA(At, 0, 1); PG8_STAGE(PG8_SB(0, 0), b2, voffB); PG8_STAGE(PG8_SB(0, 1), b2 + hstepB, voffB); PG8_STAGE(PG8_SA(0, 0), a2, voffA);
;             PG8_WAIT_V(8); PG8_WAIT_L(0); PG8_BAR; PG8_MMA(1, 0, At, B0); PG8_MMA(1, 1, At, B1); PG8_BAR; PG8_SCHED;
.LBB0_700:
	s_add_i32 s29, s28, 2
	s_add_u32 s40, s42, 0x100
	s_addc_u32 s41, s43, 0
	s_add_i32 s48, 0, 0x10000
	s_cmp_eq_u32 s25, s28
	s_cselect_b32 s47, s71, s41
	s_cselect_b32 s46, s70, s40
	s_cselect_b32 s45, s73, s27
	s_cselect_b32 s44, s72, s26
	s_add_i32 s28, 0, 0x14000
	v_add_u32_e32 v162, s48, v152
	v_add_u32_e32 v178, s28, v152
	ds_read_b128 v[144:147], v162
	ds_read_b128 v[154:157], v162 offset:1024
	ds_read_b128 v[158:161], v162 offset:2048
	ds_read_b128 v[162:165], v162 offset:3072
	ds_read_b128 v[166:169], v178
	ds_read_b128 v[170:173], v178 offset:1024
	ds_read_b128 v[174:177], v178 offset:2048
	ds_read_b128 v[178:181], v178 offset:3072
	v_lshl_add_u64 v[200:201], s[42:43], 0, v[140:141]
	s_add_i32 m0, s89, 0xc000
	ds_read_b128 v[182:185], v153
	ds_read_b128 v[186:189], v153 offset:1024
	ds_read_b128 v[190:193], v153 offset:2048
	ds_read_b128 v[194:197], v153 offset:3072
	ds_read_b128 v[206:209], v153 offset:4096
	ds_read_b128 v[210:213], v153 offset:5120
	ds_read_b128 v[222:225], v153 offset:6144
	ds_read_b128 v[226:229], v153 offset:7168
	global_load_lds_dwordx4 v[200:201], off
	v_lshl_add_u64 v[200:201], s[42:43], 0, v[142:143]
	s_add_i32 m0, s89, 0xe000
	s_nop 0
	global_load_lds_dwordx4 v[200:201], off
	s_waitcnt vmcnt(8)
	s_waitcnt lgkmcnt(0)
	s_barrier
	s_setprio 1
	s_waitcnt lgkmcnt(0)
	v_mfma_f32_16x16x32_bf16 v[126:129], v[144:147], v[182:185], v[126:129]
	v_mfma_f32_16x16x32_bf16 v[126:129], v[154:157], v[186:189], v[126:129]
	v_mfma_f32_16x16x32_bf16 v[122:125], v[158:161], v[182:185], v[122:125]
	v_mfma_f32_16x16x32_bf16 v[122:125], v[162:165], v[186:189], v[122:125]
	v_mfma_f32_16x16x32_bf16 v[110:113], v[144:147], v[190:193], v[110:113]
	v_mfma_f32_16x16x32_bf16 v[110:113], v[154:157], v[194:197], v[110:113]
	v_mfma_f32_16x16x32_bf16 v[106:109], v[158:161], v[190:193], v[106:109]
	v_mfma_f32_16x16x32_bf16 v[106:109], v[162:165], v[194:197], v[106:109]
	v_mfma_f32_16x16x32_bf16 v[92:95], v[144:147], v[206:209], v[92:95]
	v_mfma_f32_16x16x32_bf16 v[92:95], v[154:157], v[210:213], v[92:95]
	v_mfma_f32_16x16x32_bf16 v[88:91], v[158:161], v[206:209], v[88:91]
	v_mfma_f32_16x16x32_bf16 v[88:91], v[162:165], v[210:213], v[88:91]
	v_mfma_f32_16x16x32_bf16 v[76:79], v[144:147], v[222:225], v[76:79]
	v_mfma_f32_16x16x32_bf16 v[76:79], v[154:157], v[226:229], v[76:79]
	v_mfma_f32_16x16x32_bf16 v[72:75], v[158:161], v[222:225], v[72:75]
	v_mfma_f32_16x16x32_bf16 v[72:75], v[162:165], v[226:229], v[72:75]
	s_setprio 0
	s_setprio 1
	v_mfma_f32_16x16x32_bf16 v[118:121], v[166:169], v[182:185], v[118:121]
	v_mfma_f32_16x16x32_bf16 v[118:121], v[170:173], v[186:189], v[118:121]
	v_mfma_f32_16x16x32_bf16 v[114:117], v[174:177], v[182:185], v[114:117]
	v_mfma_f32_16x16x32_bf16 v[114:117], v[178:181], v[186:189], v[114:117]
	v_mfma_f32_16x16x32_bf16 v[102:105], v[166:169], v[190:193], v[102:105]
	v_mfma_f32_16x16x32_bf16 v[102:105], v[170:173], v[194:197], v[102:105]
	v_mfma_f32_16x16x32_bf16 v[98:101], v[174:177], v[190:193], v[98:101]
	v_mfma_f32_16x16x32_bf16 v[98:101], v[178:181], v[194:197], v[98:101]
	v_mfma_f32_16x16x32_bf16 v[84:87], v[166:169], v[206:209], v[84:87]
	v_mfma_f32_16x16x32_bf16 v[84:87], v[170:173], v[210:213], v[84:87]
	v_mfma_f32_16x16x32_bf16 v[80:83], v[174:177], v[206:209], v[80:83]
	v_mfma_f32_16x16x32_bf16 v[80:83], v[178:181], v[210:213], v[80:83]
	v_mfma_f32_16x16x32_bf16 v[68:71], v[166:169], v[222:225], v[68:71]
	v_mfma_f32_16x16x32_bf16 v[68:71], v[170:173], v[226:229], v[68:71]
	v_mfma_f32_16x16x32_bf16 v[64:67], v[174:177], v[222:225], v[64:67]
	v_mfma_f32_16x16x32_bf16 v[64:67], v[178:181], v[226:229], v[64:67]
	s_setprio 0
	s_barrier
	s_add_i32 s42, s48, s88
	v_lshl_add_u64 v[200:201], s[44:45], 0, v[132:133]
	s_mov_b32 m0, s42
	ds_read_b128 v[182:185], v153 offset:16384
	ds_read_b128 v[186:189], v153 offset:17408
	ds_read_b128 v[190:193], v153 offset:18432
	ds_read_b128 v[194:197], v153 offset:19456
	ds_read_b128 v[206:209], v153 offset:20480
	ds_read_b128 v[210:213], v153 offset:21504
	ds_read_b128 v[222:225], v153 offset:22528
	ds_read_b128 v[226:229], v153 offset:23552
	global_load_lds_dwordx4 v[200:201], off
	s_add_i32 m0, s42, 0x2000
	s_add_u32 s42, s44, 0x28000
	v_lshl_add_u64 v[202:203], s[44:45], 0, v[136:137]
	s_addc_u32 s43, s45, 0
	s_add_i32 s28, s28, s88
	global_load_lds_dwordx4 v[202:203], off
	v_lshl_add_u64 v[230:231], s[42:43], 0, v[132:133]
	s_mov_b32 m0, s28
	v_lshl_add_u64 v[232:233], s[46:47], 0, v[134:135]
	global_load_lds_dwordx4 v[230:231], off
	v_lshl_add_u64 v[230:231], s[42:43], 0, v[136:137]
	s_add_i32 m0, s28, 0x2000
	s_nop 0
	global_load_lds_dwordx4 v[230:231], off
	v_lshl_add_u64 v[230:231], s[46:47], 0, v[130:131]
	s_mov_b32 m0, s89
	s_nop 0
	global_load_lds_dwordx4 v[230:231], off
	s_mov_b32 m0, s90
	s_nop 0
	global_load_lds_dwordx4 v[232:233], off
	s_waitcnt vmcnt(8)
	s_waitcnt lgkmcnt(0)
	s_barrier
; #define PG8_STAGE(bufoff, gbase, voff) do { _Pragma("unroll") for (int _i = 0; _i < 2; ++_i) \
;         __builtin_amdgcn_global_load_lds((const unsigned*)((const char*)(gbase) + (voff)[_i]), (PG8_LAS unsigned*)(lds + (bufoff) + ldsw + _i * 8192), 16, 0, 0); } while (0)
; #define PG8_LDA(dst, b, h) do { _Pragma("unroll") for (int m = 0; m < 4; ++m) _Pragma("unroll") for (int k = 0; k < 2; ++k) dst[m][k] = *(const PG8_LAS bf16x8*)(lds + PG8_SA(b, h) + aoff + m * 2048 + k * 1024); } while (0)
; #define PG8_LDB(dst, b, h) do { _Pragma("unroll") for (int n = 0; n < 2; ++n) _Pragma("unroll") for (int k = 0; k < 2; ++k) dst[n][k] = *(const PG8_LAS bf16x8*)(lds + PG8_SB(b, h) + boff + n * 2048 + k * 1024); } while (0)
; #define PG8_MMA(ai, bj, At, Bt) do { __builtin_amdgcn_s_setprio(1); _Pragma("unroll") for (int m = 0; m < 4; ++m) _Pragma("unroll") for (int n = 0; n < 2; ++n) _Pragma("unroll") for (int k = 0; k < 2; ++k) \
;         acc[ai][bj][m][n] = __builtin_amdgcn_mfma_f32_16x16x32_bf16(Bt[n][k], At[m][k], acc[ai][bj][m][n], 0, 0, 0); __builtin_amdgcn_s_setprio(0); } while (0)
; #define PG8_WAIT_V(n) asm volatile("s_waitcnt vmcnt(" #n ")" ::: "memory")
; #define PG8_WAIT_L(n) asm volatile("s_waitcnt lgkmcnt(" #n ")" ::: "memory")
; #define PG8_BAR __builtin_amdgcn_s_barrier()
; #define PG8_SCHED __builtin_amdgcn_sched_barrier(0)
; template <class Epi, class Sched, bool ALIGN_EPI = true, bool SP2 = true>
; __device__ __forceinline__ void gemm_phase(PG8_LAS unsigned char* lds, const Gemm g, const Sched& S, const Epi& E, const int tid) {
;     ...
;             PG8_WAIT_V(8); PG8_WAIT_L(0); PG8_BAR; PG8_MMA(1, 0, At, B0); PG8_MMA(1, 1, At, B1); PG8_BAR; PG8_SCHED;
;             PG8_LDB(B0, 1, 0); PG8_LDB(B1, 1, 1); PG8_SCHED; PG8_LDA(At, 1, 0); PG8_STAGE(PG8_SA(0, 1), a2 + hstepA, voffA);
;             PG8_WAIT_V(8); PG8_WAIT_L(0); PG8_BAR; PG8_MMA(0, 0, At, B0); PG8_MMA(0, 1, At, B1); PG8_BAR; PG8_SCHED;
	s_setprio 1
	s_waitcnt lgkmcnt(0)
	v_mfma_f32_16x16x32_bf16 v[60:63], v[144:147], v[182:185], v[60:63]
	v_mfma_f32_16x16x32_bf16 v[60:63], v[154:157], v[186:189], v[60:63]
	v_mfma_f32_16x16x32_bf16 v[56:59], v[158:161], v[182:185], v[56:59]
	v_mfma_f32_16x16x32_bf16 v[56:59], v[162:165], v[186:189], v[56:59]
	v_mfma_f32_16x16x32_bf16 v[44:47], v[144:147], v[190:193], v[44:47]
	v_mfma_f32_16x16x32_bf16 v[44:47], v[154:157], v[194:197], v[44:47]
	v_mfma_f32_16x16x32_bf16 v[40:43], v[158:161], v[190:193], v[40:43]
	v_mfma_f32_16x16x32_bf16 v[40:43], v[162:165], v[194:197], v[40:43]
	v_mfma_f32_16x16x32_bf16 v[28:31], v[144:147], v[206:209], v[28:31]
	v_mfma_f32_16x16x32_bf16 v[28:31], v[154:157], v[210:213], v[28:31]
	v_mfma_f32_16x16x32_bf16 v[24:27], v[158:161], v[206:209], v[24:27]
	v_mfma_f32_16x16x32_bf16 v[24:27], v[162:165], v[210:213], v[24:27]
	v_mfma_f32_16x16x32_bf16 v[12:15], v[144:147], v[222:225], v[12:15]
	v_mfma_f32_16x16x32_bf16 v[12:15], v[154:157], v[226:229], v[12:15]
	v_mfma_f32_16x16x32_bf16 v[8:11], v[158:161], v[222:225], v[8:11]
	v_mfma_f32_16x16x32_bf16 v[8:11], v[162:165], v[226:229], v[8:11]
	s_setprio 0
	s_setprio 1
	v_mfma_f32_16x16x32_bf16 v[52:55], v[166:169], v[182:185], v[52:55]
	v_mfma_f32_16x16x32_bf16 v[52:55], v[170:173], v[186:189], v[52:55]
	v_mfma_f32_16x16x32_bf16 v[48:51], v[174:177], v[182:185], v[48:51]
	v_mfma_f32_16x16x32_bf16 v[48:51], v[178:181], v[186:189], v[48:51]
	v_mfma_f32_16x16x32_bf16 v[36:39], v[166:169], v[190:193], v[36:39]
	v_mfma_f32_16x16x32_bf16 v[36:39], v[170:173], v[194:197], v[36:39]
	v_mfma_f32_16x16x32_bf16 v[32:35], v[174:177], v[190:193], v[32:35]
	v_mfma_f32_16x16x32_bf16 v[32:35], v[178:181], v[194:197], v[32:35]
	v_mfma_f32_16x16x32_bf16 v[20:23], v[166:169], v[206:209], v[20:23]
	v_mfma_f32_16x16x32_bf16 v[20:23], v[170:173], v[210:213], v[20:23]
	v_mfma_f32_16x16x32_bf16 v[16:19], v[174:177], v[206:209], v[16:19]
	v_mfma_f32_16x16x32_bf16 v[16:19], v[178:181], v[210:213], v[16:19]
	v_mfma_f32_16x16x32_bf16 v[4:7], v[166:169], v[222:225], v[4:7]
	v_mfma_f32_16x16x32_bf16 v[4:7], v[170:173], v[226:229], v[4:7]
	v_mfma_f32_16x16x32_bf16 v[0:3], v[174:177], v[222:225], v[0:3]
	v_mfma_f32_16x16x32_bf16 v[0:3], v[178:181], v[226:229], v[0:3]
	s_setprio 0
	s_barrier
	s_add_i32 s28, 0, 0x18000
	s_add_i32 s48, 0, 0x1c000
	v_add_u32_e32 v162, s28, v152
	v_add_u32_e32 v178, s48, v152
	ds_read_b128 v[144:147], v162
	ds_read_b128 v[154:157], v162 offset:1024
	ds_read_b128 v[158:161], v162 offset:2048
	ds_read_b128 v[162:165], v162 offset:3072
	ds_read_b128 v[166:169], v178
	ds_read_b128 v[170:173], v178 offset:1024
	ds_read_b128 v[174:177], v178 offset:2048
	ds_read_b128 v[178:181], v178 offset:3072
	s_add_u32 s42, s46, 0x150000
	s_addc_u32 s43, s47, 0
	s_mov_b32 m0, s91
	v_lshl_add_u64 v[234:235], s[42:43], 0, v[130:131]
	ds_read_b128 v[182:185], v153 offset:32768
	ds_read_b128 v[186:189], v153 offset:33792
	ds_read_b128 v[190:193], v153 offset:34816
	ds_read_b128 v[194:197], v153 offset:35840
	ds_read_b128 v[206:209], v153 offset:36864
	ds_read_b128 v[210:213], v153 offset:37888
	ds_read_b128 v[222:225], v153 offset:38912
	ds_read_b128 v[226:229], v153 offset:39936
	global_load_lds_dwordx4 v[234:235], off
	v_lshl_add_u64 v[234:235], s[42:43], 0, v[134:135]
	s_mov_b32 m0, s80
	s_nop 0
	global_load_lds_dwordx4 v[234:235], off
	s_waitcnt vmcnt(8)
	s_waitcnt lgkmcnt(0)
	s_barrier
	s_setprio 1
	s_waitcnt lgkmcnt(0)
	v_mfma_f32_16x16x32_bf16 v[126:129], v[144:147], v[182:185], v[126:129]
	v_mfma_f32_16x16x32_bf16 v[126:129], v[154:157], v[186:189], v[126:129]
	v_mfma_f32_16x16x32_bf16 v[122:125], v[158:161], v[182:185], v[122:125]
	v_mfma_f32_16x16x32_bf16 v[122:125], v[162:165], v[186:189], v[122:125]
	v_mfma_f32_16x16x32_bf16 v[110:113], v[144:147], v[190:193], v[110:113]
	v_mfma_f32_16x16x32_bf16 v[110:113], v[154:157], v[194:197], v[110:113]
	v_mfma_f32_16x16x32_bf16 v[106:109], v[158:161], v[190:193], v[106:109]
	v_mfma_f32_16x16x32_bf16 v[106:109], v[162:165], v[194:197], v[106:109]
	v_mfma_f32_16x16x32_bf16 v[92:95], v[144:147], v[206:209], v[92:95]
	v_mfma_f32_16x16x32_bf16 v[92:95], v[154:157], v[210:213], v[92:95]
	v_mfma_f32_16x16x32_bf16 v[88:91], v[158:161], v[206:209], v[88:91]
	v_mfma_f32_16x16x32_bf16 v[88:91], v[162:165], v[210:213], v[88:91]
	v_mfma_f32_16x16x32_bf16 v[76:79], v[144:147], v[222:225], v[76:79]
	v_mfma_f32_16x16x32_bf16 v[76:79], v[154:157], v[226:229], v[76:79]
	v_mfma_f32_16x16x32_bf16 v[72:75], v[158:161], v[222:225], v[72:75]
	v_mfma_f32_16x16x32_bf16 v[72:75], v[162:165], v[226:229], v[72:75]
	s_setprio 0
	s_setprio 1
	v_mfma_f32_16x16x32_bf16 v[118:121], v[166:169], v[182:185], v[118:121]
	v_mfma_f32_16x16x32_bf16 v[118:121], v[170:173], v[186:189], v[118:121]
	v_mfma_f32_16x16x32_bf16 v[114:117], v[174:177], v[182:185], v[114:117]
	v_mfma_f32_16x16x32_bf16 v[114:117], v[178:181], v[186:189], v[114:117]
	v_mfma_f32_16x16x32_bf16 v[102:105], v[166:169], v[190:193], v[102:105]
	v_mfma_f32_16x16x32_bf16 v[102:105], v[170:173], v[194:197], v[102:105]
	v_mfma_f32_16x16x32_bf16 v[98:101], v[174:177], v[190:193], v[98:101]
	v_mfma_f32_16x16x32_bf16 v[98:101], v[178:181], v[194:197], v[98:101]
	v_mfma_f32_16x16x32_bf16 v[84:87], v[166:169], v[206:209], v[84:87]
	v_mfma_f32_16x16x32_bf16 v[84:87], v[170:173], v[210:213], v[84:87]
	v_mfma_f32_16x16x32_bf16 v[80:83], v[174:177], v[206:209], v[80:83]
	v_mfma_f32_16x16x32_bf16 v[80:83], v[178:181], v[210:213], v[80:83]
	v_mfma_f32_16x16x32_bf16 v[68:71], v[166:169], v[222:225], v[68:71]
	v_mfma_f32_16x16x32_bf16 v[68:71], v[170:173], v[226:229], v[68:71]
	v_mfma_f32_16x16x32_bf16 v[64:67], v[174:177], v[222:225], v[64:67]
	v_mfma_f32_16x16x32_bf16 v[64:67], v[178:181], v[226:229], v[64:67]
	s_setprio 0
	s_barrier
; #define PG8_STAGE(bufoff, gbase, voff) do { _Pragma("unroll") for (int _i = 0; _i < 2; ++_i) \
;         __builtin_amdgcn_global_load_lds((const unsigned*)((const char*)(gbase) + (voff)[_i]), (PG8_LAS unsigned*)(lds + (bufoff) + ldsw + _i * 8192), 16, 0, 0); } while (0)
; #define PG8_LDA(dst, b, h) do { _Pragma("unroll") for (int m = 0; m < 4; ++m) _Pragma("unroll") for (int k = 0; k < 2; ++k) dst[m][k] = *(const PG8_LAS bf16x8*)(lds + PG8_SA(b, h) + aoff + m * 2048 + k * 1024); } while (0)
; #define PG8_MMA(ai, bj, At, Bt) do { __builtin_amdgcn_s_setprio(1); _Pragma("unroll") for (int m = 0; m < 4; ++m) _Pragma("unroll") for (int n = 0; n < 2; ++n) _Pragma("unroll") for (int k = 0; k < 2; ++k) \
;         acc[ai][bj][m][n] = __builtin_amdgcn_mfma_f32_16x16x32_bf16(Bt[n][k], At[m][k], acc[ai][bj][m][n], 0, 0, 0); __builtin_amdgcn_s_setprio(0); } while (0)
; #define PG8_WAIT_V(n) asm volatile("s_waitcnt vmcnt(" #n ")" ::: "memory")
; #define PG8_WAIT_L(n) asm volatile("s_waitcnt lgkmcnt(" #n ")" ::: "memory")
; #define PG8_BAR __builtin_amdgcn_s_barrier()
; #define PG8_SCHED __builtin_amdgcn_sched_barrier(0)
; template <class Epi, class Sched, bool ALIGN_EPI = true, bool SP2 = true>
; __device__ __forceinline__ void gemm_phase(PG8_LAS unsigned char* lds, const Gemm g, const Sched& S, const Epi& E, const int tid) {
;     ...
;         for (int t = 0; t < nt; t += 2) {
;             const bool last = (t == nt - 2);
;             const char* a1 = cA + (size_t)(t + 1) * kstep;
;             const char* a2 = last ? nA : cA + (size_t)(t + 2) * kstep; const char* b2 = last ? nB : cB + (size_t)(t + 2) * kstep;
;             const char* a3 = a2 + kstep; const char* b3 = b2 + kstep;
;     ...
;             PG8_LDA(At, 1, 1); PG8_STAGE(PG8_SB(1, 0), b3, voffB); PG8_STAGE(PG8_SB(1, 1), b3 + hstepB, voffB); PG8_STAGE(PG8_SA(1, 0), a3, voffA);
;             PG8_WAIT_V(8); PG8_WAIT_L(0); PG8_BAR; PG8_MMA(1, 0, At, B0); PG8_MMA(1, 1, At, B1); PG8_BAR; PG8_SCHED;
	s_add_i32 s28, s28, s88
	v_lshl_add_u64 v[200:201], v[200:201], 0, s[4:5]
	s_mov_b32 m0, s28
	ds_read_b128 v[182:185], v153 offset:49152
	ds_read_b128 v[186:189], v153 offset:50176
	ds_read_b128 v[190:193], v153 offset:51200
	ds_read_b128 v[194:197], v153 offset:52224
	ds_read_b128 v[206:209], v153 offset:53248
	ds_read_b128 v[210:213], v153 offset:54272
	ds_read_b128 v[222:225], v153 offset:55296
	ds_read_b128 v[226:229], v153 offset:56320
	global_load_lds_dwordx4 v[200:201], off
	s_add_i32 m0, s28, 0x2000
	s_add_u32 s42, s44, 0x28080
	v_lshl_add_u64 v[200:201], v[202:203], 0, s[4:5]
	s_addc_u32 s43, s45, 0
	s_add_i32 s28, s48, s88
	global_load_lds_dwordx4 v[200:201], off
	v_lshl_add_u64 v[200:201], s[42:43], 0, v[132:133]
	s_mov_b32 m0, s28
	s_nop 0
	global_load_lds_dwordx4 v[200:201], off
	v_lshl_add_u64 v[200:201], s[42:43], 0, v[136:137]
	s_add_i32 m0, s28, 0x2000
	s_nop 0
	global_load_lds_dwordx4 v[200:201], off
	v_lshl_add_u64 v[200:201], v[230:231], 0, s[4:5]
	s_mov_b32 m0, s56
	s_nop 0
	global_load_lds_dwordx4 v[200:201], off
	v_lshl_add_u64 v[200:201], v[232:233], 0, s[4:5]
	s_mov_b32 m0, s57
	s_nop 0
	global_load_lds_dwordx4 v[200:201], off
	s_waitcnt vmcnt(8)
	s_waitcnt lgkmcnt(0)
	s_barrier
	s_setprio 1
	s_waitcnt lgkmcnt(0)
	v_mfma_f32_16x16x32_bf16 v[60:63], v[144:147], v[182:185], v[60:63]
	v_mfma_f32_16x16x32_bf16 v[60:63], v[154:157], v[186:189], v[60:63]
	v_mfma_f32_16x16x32_bf16 v[56:59], v[158:161], v[182:185], v[56:59]
	v_mfma_f32_16x16x32_bf16 v[56:59], v[162:165], v[186:189], v[56:59]
	v_mfma_f32_16x16x32_bf16 v[44:47], v[144:147], v[190:193], v[44:47]
	v_mfma_f32_16x16x32_bf16 v[44:47], v[154:157], v[194:197], v[44:47]
	v_mfma_f32_16x16x32_bf16 v[40:43], v[158:161], v[190:193], v[40:43]
	v_mfma_f32_16x16x32_bf16 v[40:43], v[162:165], v[194:197], v[40:43]
	v_mfma_f32_16x16x32_bf16 v[28:31], v[144:147], v[206:209], v[28:31]
	v_mfma_f32_16x16x32_bf16 v[28:31], v[154:157], v[210:213], v[28:31]
	v_mfma_f32_16x16x32_bf16 v[24:27], v[158:161], v[206:209], v[24:27]
	v_mfma_f32_16x16x32_bf16 v[24:27], v[162:165], v[210:213], v[24:27]
	v_mfma_f32_16x16x32_bf16 v[12:15], v[144:147], v[222:225], v[12:15]
	v_mfma_f32_16x16x32_bf16 v[12:15], v[154:157], v[226:229], v[12:15]
	v_mfma_f32_16x16x32_bf16 v[8:11], v[158:161], v[222:225], v[8:11]
	v_mfma_f32_16x16x32_bf16 v[8:11], v[162:165], v[226:229], v[8:11]
	s_setprio 0
	s_setprio 1
	v_mfma_f32_16x16x32_bf16 v[52:55], v[166:169], v[182:185], v[52:55]
	v_mfma_f32_16x16x32_bf16 v[52:55], v[170:173], v[186:189], v[52:55]
	v_mfma_f32_16x16x32_bf16 v[48:51], v[174:177], v[182:185], v[48:51]
	v_mfma_f32_16x16x32_bf16 v[48:51], v[178:181], v[186:189], v[48:51]
	v_mfma_f32_16x16x32_bf16 v[36:39], v[166:169], v[190:193], v[36:39]
	v_mfma_f32_16x16x32_bf16 v[36:39], v[170:173], v[194:197], v[36:39]
	v_mfma_f32_16x16x32_bf16 v[32:35], v[174:177], v[190:193], v[32:35]
	v_mfma_f32_16x16x32_bf16 v[32:35], v[178:181], v[194:197], v[32:35]
	v_mfma_f32_16x16x32_bf16 v[20:23], v[166:169], v[206:209], v[20:23]
	v_mfma_f32_16x16x32_bf16 v[20:23], v[170:173], v[210:213], v[20:23]
	v_mfma_f32_16x16x32_bf16 v[16:19], v[174:177], v[206:209], v[16:19]
	v_mfma_f32_16x16x32_bf16 v[16:19], v[178:181], v[210:213], v[16:19]
	v_mfma_f32_16x16x32_bf16 v[4:7], v[166:169], v[222:225], v[4:7]
	v_mfma_f32_16x16x32_bf16 v[4:7], v[170:173], v[226:229], v[4:7]
	v_mfma_f32_16x16x32_bf16 v[0:3], v[174:177], v[222:225], v[0:3]
	v_mfma_f32_16x16x32_bf16 v[0:3], v[178:181], v[226:229], v[0:3]
	s_setprio 0
	s_barrier
	s_add_u32 s26, s26, 0x100
	s_addc_u32 s27, s27, 0
	s_cmp_ge_i32 s29, s24
	s_mov_b64 s[42:43], s[40:41]
	s_mov_b32 s28, s29
	s_cbranch_scc0 .LBB0_700
	s_and_b64 vcc, exec, s[64:65]
	s_cbranch_vccz .LBB0_703
	s_barrier

; #define PG8_STAGE(bufoff, gbase, voff) do { _Pragma("unroll") for (int _i = 0; _i < 2; ++_i) \
;         __builtin_amdgcn_global_load_lds((const unsigned*)((const char*)(gbase) + (voff)[_i]), (PG8_LAS unsigned*)(lds + (bufoff) + ldsw + _i * 8192), 16, 0, 0); } while (0)
; #define PG8_LDA(dst, b, h) do { _Pragma("unroll") for (int m = 0; m < 4; ++m) _Pragma("unroll") for (int k = 0; k < 2; ++k) dst[m][k] = *(const PG8_LAS bf16x8*)(lds + PG8_SA(b, h) + aoff + m * 2048 + k * 1024); } while (0)
; #define PG8_LDB(dst, b, h) do { _Pragma("unroll") for (int n = 0; n < 2; ++n) _Pragma("unroll") for (int k = 0; k < 2; ++k) dst[n][k] = *(const PG8_LAS bf16x8*)(lds + PG8_SB(b, h) + boff + n * 2048 + k * 1024); } while (0)
; #define PG8_MMA(ai, bj, At, Bt) do { __builtin_amdgcn_s_setprio(1); _Pragma("unroll") for (int m = 0; m < 4; ++m) _Pragma("unroll") for (int n = 0; n < 2; ++n) _Pragma("unroll") for (int k = 0; k < 2; ++k) \
;         acc[ai][bj][m][n] = __builtin_amdgcn_mfma_f32_16x16x32_bf16(Bt[n][k], At[m][k], acc[ai][bj][m][n], 0, 0, 0); __builtin_amdgcn_s_setprio(0); } while (0)
; #define PG8_WAIT_V(n) asm volatile("s_waitcnt vmcnt(" #n ")" ::: "memory")
; #define PG8_WAIT_L(n) asm volatile("s_waitcnt lgkmcnt(" #n ")" ::: "memory")
; template <class Epi, class Sched, bool ALIGN_EPI = true, bool SP2 = true>
; __device__ __forceinline__ void gemm_phase(PG8_LAS unsigned char* lds, const Gemm g, const Sched& S, const Epi& E, const int tid) {
;     ...
;             const bool last = (t == nt - 2);
;             const char* a1 = cA + (size_t)(t + 1) * kstep;
;             const char* a2 = last ? nA : cA + (size_t)(t + 2) * kstep; const char* b2 = last ? nB : cB + (size_t)(t + 2) * kstep;
;             const char* a3 = a2 + kstep; const char* b3 = b2 + kstep;
;             if (last && has_next) S.a_ready(nxt);
;             if constexpr (SP2) {
;             PG8_LDB(B0, 0, 0); PG8_LDB(B1, 0, 1); PG8_SCHED; PG8_LDA(At, 0, 0); PG8_STAGE(PG8_SA(1, 1), a1 + hstepA, voffA);
;             PG8_WAIT_V(8); PG8_WAIT_L(0); PG8_BAR; PG8_MMA(0, 0, At, B0); PG8_MMA(0, 1, At, B1); PG8_BAR; PG8_SCHED;
;             PG8_LDA(At, 0, 1); PG8_STAGE(PG8_SB(0, 0), b2, voffB); PG8_STAGE(PG8_SB(0, 1), b2 + hstepB, voffB); PG8_STAGE(PG8_SA(0, 0), a2, voffA);
;             PG8_WAIT_V(8); PG8_WAIT_L(0); PG8_BAR; PG8_MMA(1, 0, At, B0); PG8_MMA(1, 1, At, B1); PG8_BAR; PG8_SCHED;
.LBB0_1077:
	s_add_i32 s63, s82, 2
	s_add_u32 s83, s80, 0xfff80080
	s_addc_u32 s84, s81, -1
	s_add_i32 vcc_lo, 0, 0x10000
	s_cmp_eq_u32 s29, s82
	s_cselect_b32 s85, s67, s84
	s_cselect_b32 s84, s66, s83
	v_add_u32_e32 v96, vcc_lo, v141
	s_cselect_b32 s83, s69, s61
	s_cselect_b32 s82, s68, s59
	s_add_i32 s30, 0, 0x14000
	ds_read_b128 v[146:149], v96
	ds_read_b128 v[150:153], v96 offset:1024
	ds_read_b128 v[154:157], v96 offset:2048
	ds_read_b128 v[158:161], v96 offset:3072
	v_add_u32_e32 v96, s30, v141
	ds_read_b128 v[162:165], v96
	ds_read_b128 v[166:169], v96 offset:1024
	ds_read_b128 v[170:173], v96 offset:2048
	ds_read_b128 v[174:177], v96 offset:3072
	v_lshl_add_u64 v[98:99], s[80:81], 0, v[136:137]
	s_add_i32 m0, s25, 0xc000
	ds_read_b128 v[178:181], v145
	ds_read_b128 v[182:185], v145 offset:1024
	ds_read_b128 v[186:189], v145 offset:2048
	ds_read_b128 v[190:193], v145 offset:3072
	ds_read_b128 v[194:197], v145 offset:4096
	ds_read_b128 v[200:203], v145 offset:5120
	ds_read_b128 v[206:209], v145 offset:6144
	ds_read_b128 v[210:213], v145 offset:7168
	global_load_lds_dwordx4 v[98:99], off
	v_lshl_add_u64 v[98:99], s[80:81], 0, v[138:139]
	s_add_i32 m0, s25, 0xe000
	s_nop 0
	global_load_lds_dwordx4 v[98:99], off
	s_waitcnt vmcnt(8)
	s_waitcnt lgkmcnt(0)
	s_barrier
	s_setprio 1
	s_waitcnt lgkmcnt(0)
	v_mfma_f32_16x16x32_bf16 v[92:95], v[146:149], v[178:181], v[92:95]
	v_mfma_f32_16x16x32_bf16 v[92:95], v[150:153], v[182:185], v[92:95]
	v_mfma_f32_16x16x32_bf16 v[130:133], v[154:157], v[178:181], v[130:133]
	v_mfma_f32_16x16x32_bf16 v[130:133], v[158:161], v[182:185], v[130:133]
	v_mfma_f32_16x16x32_bf16 v[126:129], v[146:149], v[186:189], v[126:129]
	v_mfma_f32_16x16x32_bf16 v[126:129], v[150:153], v[190:193], v[126:129]
	v_mfma_f32_16x16x32_bf16 v[122:125], v[154:157], v[186:189], v[122:125]
	v_mfma_f32_16x16x32_bf16 v[122:125], v[158:161], v[190:193], v[122:125]
	v_mfma_f32_16x16x32_bf16 v[118:121], v[146:149], v[194:197], v[118:121]
	v_mfma_f32_16x16x32_bf16 v[118:121], v[150:153], v[200:203], v[118:121]
	v_mfma_f32_16x16x32_bf16 v[110:113], v[154:157], v[194:197], v[110:113]
	v_mfma_f32_16x16x32_bf16 v[110:113], v[158:161], v[200:203], v[110:113]
	v_mfma_f32_16x16x32_bf16 v[76:79], v[146:149], v[206:209], v[76:79]
	v_mfma_f32_16x16x32_bf16 v[76:79], v[150:153], v[210:213], v[76:79]
	v_mfma_f32_16x16x32_bf16 v[72:75], v[154:157], v[206:209], v[72:75]
	v_mfma_f32_16x16x32_bf16 v[72:75], v[158:161], v[210:213], v[72:75]
	s_setprio 0
	s_setprio 1
	v_mfma_f32_16x16x32_bf16 v[88:91], v[162:165], v[178:181], v[88:91]
	v_mfma_f32_16x16x32_bf16 v[88:91], v[166:169], v[182:185], v[88:91]
	v_mfma_f32_16x16x32_bf16 v[84:87], v[170:173], v[178:181], v[84:87]
	v_mfma_f32_16x16x32_bf16 v[84:87], v[174:177], v[182:185], v[84:87]
	v_mfma_f32_16x16x32_bf16 v[114:117], v[162:165], v[186:189], v[114:117]
	v_mfma_f32_16x16x32_bf16 v[114:117], v[166:169], v[190:193], v[114:117]
	v_mfma_f32_16x16x32_bf16 v[106:109], v[170:173], v[186:189], v[106:109]
	v_mfma_f32_16x16x32_bf16 v[106:109], v[174:177], v[190:193], v[106:109]
	v_mfma_f32_16x16x32_bf16 v[102:105], v[162:165], v[194:197], v[102:105]
	v_mfma_f32_16x16x32_bf16 v[102:105], v[166:169], v[200:203], v[102:105]
	v_mfma_f32_16x16x32_bf16 v[80:83], v[170:173], v[194:197], v[80:83]
	v_mfma_f32_16x16x32_bf16 v[80:83], v[174:177], v[200:203], v[80:83]
	v_mfma_f32_16x16x32_bf16 v[68:71], v[162:165], v[206:209], v[68:71]
	v_mfma_f32_16x16x32_bf16 v[68:71], v[166:169], v[210:213], v[68:71]
	v_mfma_f32_16x16x32_bf16 v[64:67], v[170:173], v[206:209], v[64:67]
	v_mfma_f32_16x16x32_bf16 v[64:67], v[174:177], v[210:213], v[64:67]
	s_setprio 0
	s_barrier
	s_add_i32 s31, vcc_lo, s24
	v_lshl_add_u64 v[98:99], s[82:83], 0, v[100:101]
	s_mov_b32 m0, s31
	ds_read_b128 v[178:181], v145 offset:16384
	ds_read_b128 v[182:185], v145 offset:17408
	ds_read_b128 v[186:189], v145 offset:18432
	ds_read_b128 v[190:193], v145 offset:19456
	ds_read_b128 v[194:197], v145 offset:20480
	ds_read_b128 v[200:203], v145 offset:21504
	ds_read_b128 v[206:209], v145 offset:22528
	ds_read_b128 v[210:213], v145 offset:23552
	global_load_lds_dwordx4 v[98:99], off
	s_add_i32 m0, s31, 0x2000
	s_add_u32 vcc_lo, s82, 0x80000
	v_lshl_add_u64 v[224:225], s[82:83], 0, v[134:135]
	s_addc_u32 vcc_hi, s83, 0
	s_add_i32 s30, s30, s24
	global_load_lds_dwordx4 v[224:225], off
	v_lshl_add_u64 v[226:227], vcc, 0, v[100:101]
	s_mov_b32 m0, s30
	v_lshl_add_u64 v[228:229], s[84:85], 0, v[134:135]
	global_load_lds_dwordx4 v[226:227], off
	v_lshl_add_u64 v[226:227], vcc, 0, v[134:135]
	s_add_i32 m0, s30, 0x2000
	s_nop 0
	global_load_lds_dwordx4 v[226:227], off
	v_lshl_add_u64 v[226:227], s[84:85], 0, v[100:101]
	s_mov_b32 m0, s25
	s_nop 0
	global_load_lds_dwordx4 v[226:227], off
	s_mov_b32 m0, s49
	s_nop 0
	global_load_lds_dwordx4 v[228:229], off
	s_waitcnt vmcnt(8)
	s_waitcnt lgkmcnt(0)
	s_barrier
; #define PG8_STAGE(bufoff, gbase, voff) do { _Pragma("unroll") for (int _i = 0; _i < 2; ++_i) \
;         __builtin_amdgcn_global_load_lds((const unsigned*)((const char*)(gbase) + (voff)[_i]), (PG8_LAS unsigned*)(lds + (bufoff) + ldsw + _i * 8192), 16, 0, 0); } while (0)
; #define PG8_LDA(dst, b, h) do { _Pragma("unroll") for (int m = 0; m < 4; ++m) _Pragma("unroll") for (int k = 0; k < 2; ++k) dst[m][k] = *(const PG8_LAS bf16x8*)(lds + PG8_SA(b, h) + aoff + m * 2048 + k * 1024); } while (0)
; #define PG8_LDB(dst, b, h) do { _Pragma("unroll") for (int n = 0; n < 2; ++n) _Pragma("unroll") for (int k = 0; k < 2; ++k) dst[n][k] = *(const PG8_LAS bf16x8*)(lds + PG8_SB(b, h) + boff + n * 2048 + k * 1024); } while (0)
; #define PG8_MMA(ai, bj, At, Bt) do { __builtin_amdgcn_s_setprio(1); _Pragma("unroll") for (int m = 0; m < 4; ++m) _Pragma("unroll") for (int n = 0; n < 2; ++n) _Pragma("unroll") for (int k = 0; k < 2; ++k) \
;         acc[ai][bj][m][n] = __builtin_amdgcn_mfma_f32_16x16x32_bf16(Bt[n][k], At[m][k], acc[ai][bj][m][n], 0, 0, 0); __builtin_amdgcn_s_setprio(0); } while (0)
; #define PG8_WAIT_V(n) asm volatile("s_waitcnt vmcnt(" #n ")" ::: "memory")
; #define PG8_WAIT_L(n) asm volatile("s_waitcnt lgkmcnt(" #n ")" ::: "memory")
; #define PG8_BAR __builtin_amdgcn_s_barrier()
; #define PG8_SCHED __builtin_amdgcn_sched_barrier(0)
; template <class Epi, class Sched, bool ALIGN_EPI = true, bool SP2 = true>
; __device__ __forceinline__ void gemm_phase(PG8_LAS unsigned char* lds, const Gemm g, const Sched& S, const Epi& E, const int tid) {
;     ...
;             PG8_WAIT_V(8); PG8_WAIT_L(0); PG8_BAR; PG8_MMA(1, 0, At, B0); PG8_MMA(1, 1, At, B1); PG8_BAR; PG8_SCHED;
;             PG8_LDB(B0, 1, 0); PG8_LDB(B1, 1, 1); PG8_SCHED; PG8_LDA(At, 1, 0); PG8_STAGE(PG8_SA(0, 1), a2 + hstepA, voffA);
;             PG8_WAIT_V(8); PG8_WAIT_L(0); PG8_BAR; PG8_MMA(0, 0, At, B0); PG8_MMA(0, 1, At, B1); PG8_BAR; PG8_SCHED;
	s_setprio 1
	s_waitcnt lgkmcnt(0)
	v_mfma_f32_16x16x32_bf16 v[56:59], v[146:149], v[178:181], v[56:59]
	v_mfma_f32_16x16x32_bf16 v[56:59], v[150:153], v[182:185], v[56:59]
	v_mfma_f32_16x16x32_bf16 v[60:63], v[154:157], v[178:181], v[60:63]
	v_mfma_f32_16x16x32_bf16 v[60:63], v[158:161], v[182:185], v[60:63]
	v_mfma_f32_16x16x32_bf16 v[44:47], v[146:149], v[186:189], v[44:47]
	v_mfma_f32_16x16x32_bf16 v[44:47], v[150:153], v[190:193], v[44:47]
	v_mfma_f32_16x16x32_bf16 v[40:43], v[154:157], v[186:189], v[40:43]
	v_mfma_f32_16x16x32_bf16 v[40:43], v[158:161], v[190:193], v[40:43]
	v_mfma_f32_16x16x32_bf16 v[28:31], v[146:149], v[194:197], v[28:31]
	v_mfma_f32_16x16x32_bf16 v[28:31], v[150:153], v[200:203], v[28:31]
	v_mfma_f32_16x16x32_bf16 v[24:27], v[154:157], v[194:197], v[24:27]
	v_mfma_f32_16x16x32_bf16 v[24:27], v[158:161], v[200:203], v[24:27]
	v_mfma_f32_16x16x32_bf16 v[12:15], v[146:149], v[206:209], v[12:15]
	v_mfma_f32_16x16x32_bf16 v[12:15], v[150:153], v[210:213], v[12:15]
	v_mfma_f32_16x16x32_bf16 v[8:11], v[154:157], v[206:209], v[8:11]
	v_mfma_f32_16x16x32_bf16 v[8:11], v[158:161], v[210:213], v[8:11]
	s_setprio 0
	s_setprio 1
	v_mfma_f32_16x16x32_bf16 v[52:55], v[162:165], v[178:181], v[52:55]
	v_mfma_f32_16x16x32_bf16 v[52:55], v[166:169], v[182:185], v[52:55]
	v_mfma_f32_16x16x32_bf16 v[48:51], v[170:173], v[178:181], v[48:51]
	v_mfma_f32_16x16x32_bf16 v[48:51], v[174:177], v[182:185], v[48:51]
	v_mfma_f32_16x16x32_bf16 v[36:39], v[162:165], v[186:189], v[36:39]
	v_mfma_f32_16x16x32_bf16 v[36:39], v[166:169], v[190:193], v[36:39]
	v_mfma_f32_16x16x32_bf16 v[32:35], v[170:173], v[186:189], v[32:35]
	v_mfma_f32_16x16x32_bf16 v[32:35], v[174:177], v[190:193], v[32:35]
	v_mfma_f32_16x16x32_bf16 v[20:23], v[162:165], v[194:197], v[20:23]
	v_mfma_f32_16x16x32_bf16 v[20:23], v[166:169], v[200:203], v[20:23]
	v_mfma_f32_16x16x32_bf16 v[16:19], v[170:173], v[194:197], v[16:19]
	v_mfma_f32_16x16x32_bf16 v[16:19], v[174:177], v[200:203], v[16:19]
	v_mfma_f32_16x16x32_bf16 v[4:7], v[162:165], v[206:209], v[4:7]
	v_mfma_f32_16x16x32_bf16 v[4:7], v[166:169], v[210:213], v[4:7]
	v_mfma_f32_16x16x32_bf16 v[0:3], v[170:173], v[206:209], v[0:3]
	v_mfma_f32_16x16x32_bf16 v[0:3], v[174:177], v[210:213], v[0:3]
	s_setprio 0
	s_barrier
	s_add_i32 s30, 0, 0x18000
	v_add_u32_e32 v96, s30, v141
	s_add_i32 s31, 0, 0x1c000
	ds_read_b128 v[146:149], v96
	ds_read_b128 v[150:153], v96 offset:1024
	ds_read_b128 v[154:157], v96 offset:2048
	ds_read_b128 v[158:161], v96 offset:3072
	v_add_u32_e32 v96, s31, v141
	ds_read_b128 v[162:165], v96
	ds_read_b128 v[166:169], v96 offset:1024
	ds_read_b128 v[170:173], v96 offset:2048
	ds_read_b128 v[174:177], v96 offset:3072
	s_add_u32 s84, s84, 0x80000
	s_addc_u32 s85, s85, 0
	s_mov_b32 m0, s51
	v_lshl_add_u64 v[230:231], s[84:85], 0, v[100:101]
	ds_read_b128 v[178:181], v145 offset:32768
	ds_read_b128 v[182:185], v145 offset:33792
	ds_read_b128 v[186:189], v145 offset:34816
	ds_read_b128 v[190:193], v145 offset:35840
	ds_read_b128 v[194:197], v145 offset:36864
	ds_read_b128 v[200:203], v145 offset:37888
	ds_read_b128 v[206:209], v145 offset:38912
	ds_read_b128 v[210:213], v145 offset:39936
	global_load_lds_dwordx4 v[230:231], off
	v_lshl_add_u64 v[230:231], s[84:85], 0, v[134:135]
	s_mov_b32 m0, s76
	s_nop 0
	global_load_lds_dwordx4 v[230:231], off
	s_waitcnt vmcnt(8)
	s_waitcnt lgkmcnt(0)
	s_barrier
	s_setprio 1
	s_waitcnt lgkmcnt(0)
	v_mfma_f32_16x16x32_bf16 v[92:95], v[146:149], v[178:181], v[92:95]
	v_mfma_f32_16x16x32_bf16 v[92:95], v[150:153], v[182:185], v[92:95]
	v_mfma_f32_16x16x32_bf16 v[130:133], v[154:157], v[178:181], v[130:133]
	v_mfma_f32_16x16x32_bf16 v[130:133], v[158:161], v[182:185], v[130:133]
	v_mfma_f32_16x16x32_bf16 v[126:129], v[146:149], v[186:189], v[126:129]
	v_mfma_f32_16x16x32_bf16 v[126:129], v[150:153], v[190:193], v[126:129]
	v_mfma_f32_16x16x32_bf16 v[122:125], v[154:157], v[186:189], v[122:125]
	v_mfma_f32_16x16x32_bf16 v[122:125], v[158:161], v[190:193], v[122:125]
	v_mfma_f32_16x16x32_bf16 v[118:121], v[146:149], v[194:197], v[118:121]
	v_mfma_f32_16x16x32_bf16 v[118:121], v[150:153], v[200:203], v[118:121]
	v_mfma_f32_16x16x32_bf16 v[110:113], v[154:157], v[194:197], v[110:113]
	v_mfma_f32_16x16x32_bf16 v[110:113], v[158:161], v[200:203], v[110:113]
	v_mfma_f32_16x16x32_bf16 v[76:79], v[146:149], v[206:209], v[76:79]
	v_mfma_f32_16x16x32_bf16 v[76:79], v[150:153], v[210:213], v[76:79]
	v_mfma_f32_16x16x32_bf16 v[72:75], v[154:157], v[206:209], v[72:75]
	v_mfma_f32_16x16x32_bf16 v[72:75], v[158:161], v[210:213], v[72:75]
	s_setprio 0
	s_setprio 1
	v_mfma_f32_16x16x32_bf16 v[88:91], v[162:165], v[178:181], v[88:91]
	v_mfma_f32_16x16x32_bf16 v[88:91], v[166:169], v[182:185], v[88:91]
	v_mfma_f32_16x16x32_bf16 v[84:87], v[170:173], v[178:181], v[84:87]
	v_mfma_f32_16x16x32_bf16 v[84:87], v[174:177], v[182:185], v[84:87]
	v_mfma_f32_16x16x32_bf16 v[114:117], v[162:165], v[186:189], v[114:117]
	v_mfma_f32_16x16x32_bf16 v[114:117], v[166:169], v[190:193], v[114:117]
	v_mfma_f32_16x16x32_bf16 v[106:109], v[170:173], v[186:189], v[106:109]
	v_mfma_f32_16x16x32_bf16 v[106:109], v[174:177], v[190:193], v[106:109]
	v_mfma_f32_16x16x32_bf16 v[102:105], v[162:165], v[194:197], v[102:105]
	v_mfma_f32_16x16x32_bf16 v[102:105], v[166:169], v[200:203], v[102:105]
	v_mfma_f32_16x16x32_bf16 v[80:83], v[170:173], v[194:197], v[80:83]
	v_mfma_f32_16x16x32_bf16 v[80:83], v[174:177], v[200:203], v[80:83]
	v_mfma_f32_16x16x32_bf16 v[68:71], v[162:165], v[206:209], v[68:71]
	v_mfma_f32_16x16x32_bf16 v[68:71], v[166:169], v[210:213], v[68:71]
	v_mfma_f32_16x16x32_bf16 v[64:67], v[170:173], v[206:209], v[64:67]
	v_mfma_f32_16x16x32_bf16 v[64:67], v[174:177], v[210:213], v[64:67]
	s_setprio 0
	s_barrier
; #define PG8_STAGE(bufoff, gbase, voff) do { _Pragma("unroll") for (int _i = 0; _i < 2; ++_i) \
;         __builtin_amdgcn_global_load_lds((const unsigned*)((const char*)(gbase) + (voff)[_i]), (PG8_LAS unsigned*)(lds + (bufoff) + ldsw + _i * 8192), 16, 0, 0); } while (0)
; #define PG8_LDA(dst, b, h) do { _Pragma("unroll") for (int m = 0; m < 4; ++m) _Pragma("unroll") for (int k = 0; k < 2; ++k) dst[m][k] = *(const PG8_LAS bf16x8*)(lds + PG8_SA(b, h) + aoff + m * 2048 + k * 1024); } while (0)
; #define PG8_MMA(ai, bj, At, Bt) do { __builtin_amdgcn_s_setprio(1); _Pragma("unroll") for (int m = 0; m < 4; ++m) _Pragma("unroll") for (int n = 0; n < 2; ++n) _Pragma("unroll") for (int k = 0; k < 2; ++k) \
;         acc[ai][bj][m][n] = __builtin_amdgcn_mfma_f32_16x16x32_bf16(Bt[n][k], At[m][k], acc[ai][bj][m][n], 0, 0, 0); __builtin_amdgcn_s_setprio(0); } while (0)
; #define PG8_WAIT_V(n) asm volatile("s_waitcnt vmcnt(" #n ")" ::: "memory")
; #define PG8_WAIT_L(n) asm volatile("s_waitcnt lgkmcnt(" #n ")" ::: "memory")
; #define PG8_BAR __builtin_amdgcn_s_barrier()
; #define PG8_SCHED __builtin_amdgcn_sched_barrier(0)
; template <class Epi, class Sched, bool ALIGN_EPI = true, bool SP2 = true>
; __device__ __forceinline__ void gemm_phase(PG8_LAS unsigned char* lds, const Gemm g, const Sched& S, const Epi& E, const int tid) {
;     ...
;         for (int t = 0; t < nt; t += 2) {
;             const bool last = (t == nt - 2);
;             const char* a1 = cA + (size_t)(t + 1) * kstep;
;             const char* a2 = last ? nA : cA + (size_t)(t + 2) * kstep; const char* b2 = last ? nB : cB + (size_t)(t + 2) * kstep;
;             const char* a3 = a2 + kstep; const char* b3 = b2 + kstep;
;     ...
;             PG8_LDA(At, 1, 1); PG8_STAGE(PG8_SB(1, 0), b3, voffB); PG8_STAGE(PG8_SB(1, 1), b3 + hstepB, voffB); PG8_STAGE(PG8_SA(1, 0), a3, voffA);
;             PG8_WAIT_V(8); PG8_WAIT_L(0); PG8_BAR; PG8_MMA(1, 0, At, B0); PG8_MMA(1, 1, At, B1); PG8_BAR; PG8_SCHED;
	s_add_i32 s30, s30, s24
	v_lshl_add_u64 v[98:99], v[98:99], 0, s[4:5]
	s_mov_b32 m0, s30
	ds_read_b128 v[178:181], v145 offset:49152
	ds_read_b128 v[182:185], v145 offset:50176
	ds_read_b128 v[186:189], v145 offset:51200
	ds_read_b128 v[190:193], v145 offset:52224
	ds_read_b128 v[194:197], v145 offset:53248
	ds_read_b128 v[200:203], v145 offset:54272
	ds_read_b128 v[206:209], v145 offset:55296
	ds_read_b128 v[210:213], v145 offset:56320
	global_load_lds_dwordx4 v[98:99], off
	s_add_i32 m0, s30, 0x2000
	s_add_u32 s82, s82, 0x80080
	v_lshl_add_u64 v[98:99], v[224:225], 0, s[4:5]
	s_addc_u32 s83, s83, 0
	s_add_i32 s30, s31, s24
	global_load_lds_dwordx4 v[98:99], off
	v_lshl_add_u64 v[98:99], s[82:83], 0, v[100:101]
	s_mov_b32 m0, s30
	s_nop 0
	global_load_lds_dwordx4 v[98:99], off
	v_lshl_add_u64 v[98:99], s[82:83], 0, v[134:135]
	s_add_i32 m0, s30, 0x2000
	s_nop 0
	global_load_lds_dwordx4 v[98:99], off
	v_lshl_add_u64 v[98:99], v[226:227], 0, s[4:5]
	s_mov_b32 m0, s90
	s_nop 0
	global_load_lds_dwordx4 v[98:99], off
	v_lshl_add_u64 v[98:99], v[228:229], 0, s[4:5]
	s_mov_b32 m0, s91
	s_nop 0
	global_load_lds_dwordx4 v[98:99], off
	s_waitcnt vmcnt(8)
	s_waitcnt lgkmcnt(0)
	s_barrier
	s_setprio 1
	s_waitcnt lgkmcnt(0)
	v_mfma_f32_16x16x32_bf16 v[56:59], v[146:149], v[178:181], v[56:59]
	v_mfma_f32_16x16x32_bf16 v[56:59], v[150:153], v[182:185], v[56:59]
	v_mfma_f32_16x16x32_bf16 v[60:63], v[154:157], v[178:181], v[60:63]
	v_mfma_f32_16x16x32_bf16 v[60:63], v[158:161], v[182:185], v[60:63]
	v_mfma_f32_16x16x32_bf16 v[44:47], v[146:149], v[186:189], v[44:47]
	v_mfma_f32_16x16x32_bf16 v[44:47], v[150:153], v[190:193], v[44:47]
	v_mfma_f32_16x16x32_bf16 v[40:43], v[154:157], v[186:189], v[40:43]
	v_mfma_f32_16x16x32_bf16 v[40:43], v[158:161], v[190:193], v[40:43]
	v_mfma_f32_16x16x32_bf16 v[28:31], v[146:149], v[194:197], v[28:31]
	v_mfma_f32_16x16x32_bf16 v[28:31], v[150:153], v[200:203], v[28:31]
	v_mfma_f32_16x16x32_bf16 v[24:27], v[154:157], v[194:197], v[24:27]
	v_mfma_f32_16x16x32_bf16 v[24:27], v[158:161], v[200:203], v[24:27]
	v_mfma_f32_16x16x32_bf16 v[12:15], v[146:149], v[206:209], v[12:15]
	v_mfma_f32_16x16x32_bf16 v[12:15], v[150:153], v[210:213], v[12:15]
	v_mfma_f32_16x16x32_bf16 v[8:11], v[154:157], v[206:209], v[8:11]
	v_mfma_f32_16x16x32_bf16 v[8:11], v[158:161], v[210:213], v[8:11]
	s_setprio 0
	s_setprio 1
	v_mfma_f32_16x16x32_bf16 v[52:55], v[162:165], v[178:181], v[52:55]
	v_mfma_f32_16x16x32_bf16 v[52:55], v[166:169], v[182:185], v[52:55]
	v_mfma_f32_16x16x32_bf16 v[48:51], v[170:173], v[178:181], v[48:51]
	v_mfma_f32_16x16x32_bf16 v[48:51], v[174:177], v[182:185], v[48:51]
	v_mfma_f32_16x16x32_bf16 v[36:39], v[162:165], v[186:189], v[36:39]
	v_mfma_f32_16x16x32_bf16 v[36:39], v[166:169], v[190:193], v[36:39]
	v_mfma_f32_16x16x32_bf16 v[32:35], v[170:173], v[186:189], v[32:35]
	v_mfma_f32_16x16x32_bf16 v[32:35], v[174:177], v[190:193], v[32:35]
	v_mfma_f32_16x16x32_bf16 v[20:23], v[162:165], v[194:197], v[20:23]
	v_mfma_f32_16x16x32_bf16 v[20:23], v[166:169], v[200:203], v[20:23]
	v_mfma_f32_16x16x32_bf16 v[16:19], v[170:173], v[194:197], v[16:19]
	v_mfma_f32_16x16x32_bf16 v[16:19], v[174:177], v[200:203], v[16:19]
	v_mfma_f32_16x16x32_bf16 v[4:7], v[162:165], v[206:209], v[4:7]
	v_mfma_f32_16x16x32_bf16 v[4:7], v[166:169], v[210:213], v[4:7]
	v_mfma_f32_16x16x32_bf16 v[0:3], v[170:173], v[206:209], v[0:3]
	v_mfma_f32_16x16x32_bf16 v[0:3], v[174:177], v[210:213], v[0:3]
	s_setprio 0
	s_barrier
	s_add_u32 s80, s80, 0x100
	s_addc_u32 s81, s81, 0
	s_add_u32 s59, s59, 0x100
	s_addc_u32 s61, s61, 0
	s_cmp_ge_i32 s63, s57
	s_mov_b32 s82, s63
	s_cbranch_scc0 .LBB0_1077

; #define PG8_STAGE(bufoff, gbase, voff) do { _Pragma("unroll") for (int _i = 0; _i < 2; ++_i) \
;         __builtin_amdgcn_global_load_lds((const unsigned*)((const char*)(gbase) + (voff)[_i]), (PG8_LAS unsigned*)(lds + (bufoff) + ldsw + _i * 8192), 16, 0, 0); } while (0)
; #define PG8_LDA(dst, b, h) do { _Pragma("unroll") for (int m = 0; m < 4; ++m) _Pragma("unroll") for (int k = 0; k < 2; ++k) dst[m][k] = *(const PG8_LAS bf16x8*)(lds + PG8_SA(b, h) + aoff + m * 2048 + k * 1024); } while (0)
; #define PG8_LDB(dst, b, h) do { _Pragma("unroll") for (int n = 0; n < 2; ++n) _Pragma("unroll") for (int k = 0; k < 2; ++k) dst[n][k] = *(const PG8_LAS bf16x8*)(lds + PG8_SB(b, h) + boff + n * 2048 + k * 1024); } while (0)
; #define PG8_MMA(ai, bj, At, Bt) do { __builtin_amdgcn_s_setprio(1); _Pragma("unroll") for (int m = 0; m < 4; ++m) _Pragma("unroll") for (int n = 0; n < 2; ++n) _Pragma("unroll") for (int k = 0; k < 2; ++k) \
;         acc[ai][bj][m][n] = __builtin_amdgcn_mfma_f32_16x16x32_bf16(Bt[n][k], At[m][k], acc[ai][bj][m][n], 0, 0, 0); __builtin_amdgcn_s_setprio(0); } while (0)
; #define PG8_WAIT_V(n) asm volatile("s_waitcnt vmcnt(" #n ")" ::: "memory")
; #define PG8_WAIT_L(n) asm volatile("s_waitcnt lgkmcnt(" #n ")" ::: "memory")
; template <class Epi, class Sched, bool ALIGN_EPI = true, bool SP2 = true>
; __device__ __forceinline__ void gemm_phase(PG8_LAS unsigned char* lds, const Gemm g, const Sched& S, const Epi& E, const int tid) {
;     ...
;             const bool last = (t == nt - 2);
;             const char* a1 = cA + (size_t)(t + 1) * kstep;
;             const char* a2 = last ? nA : cA + (size_t)(t + 2) * kstep; const char* b2 = last ? nB : cB + (size_t)(t + 2) * kstep;
;             const char* a3 = a2 + kstep; const char* b3 = b2 + kstep;
;             if (last && has_next) S.a_ready(nxt);
;             if constexpr (SP2) {
;             PG8_LDB(B0, 0, 0); PG8_LDB(B1, 0, 1); PG8_SCHED; PG8_LDA(At, 0, 0); PG8_STAGE(PG8_SA(1, 1), a1 + hstepA, voffA);
;             PG8_WAIT_V(8); PG8_WAIT_L(0); PG8_BAR; PG8_MMA(0, 0, At, B0); PG8_MMA(0, 1, At, B1); PG8_BAR; PG8_SCHED;
;             PG8_LDA(At, 0, 1); PG8_STAGE(PG8_SB(0, 0), b2, voffB); PG8_STAGE(PG8_SB(0, 1), b2 + hstepB, voffB); PG8_STAGE(PG8_SA(0, 0), a2, voffA);
;             PG8_WAIT_V(8); PG8_WAIT_L(0); PG8_BAR; PG8_MMA(1, 0, At, B0); PG8_MMA(1, 1, At, B1); PG8_BAR; PG8_SCHED;
.LBB0_1319:
	s_add_u32 s28, s62, 0xfff80080
	s_addc_u32 s29, s63, -1
	s_add_i32 s30, 0, 0x10000
	s_cmp_eq_u32 s52, 28
	s_cselect_b32 s67, s24, s29
	s_cselect_b32 s66, s25, s28
	v_add_u32_e32 v145, s30, v142
	s_cselect_b32 s65, s26, s51
	s_cselect_b32 s64, s27, s49
	s_add_i32 s31, 0, 0x14000
	ds_read_b128 v[146:149], v145
	ds_read_b128 v[150:153], v145 offset:1024
	ds_read_b128 v[154:157], v145 offset:2048
	ds_read_b128 v[158:161], v145 offset:3072
	v_add_u32_e32 v145, s31, v142
	ds_read_b128 v[162:165], v145
	ds_read_b128 v[166:169], v145 offset:1024
	ds_read_b128 v[170:173], v145 offset:2048
	ds_read_b128 v[174:177], v145 offset:3072
	v_lshl_add_u64 v[222:223], s[62:63], 0, v[138:139]
	s_add_i32 m0, s22, 0xc000
	ds_read_b128 v[178:181], v144
	ds_read_b128 v[182:185], v144 offset:1024
	ds_read_b128 v[186:189], v144 offset:2048
	ds_read_b128 v[190:193], v144 offset:3072
	ds_read_b128 v[194:197], v144 offset:4096
	ds_read_b128 v[200:203], v144 offset:5120
	ds_read_b128 v[206:209], v144 offset:6144
	ds_read_b128 v[210:213], v144 offset:7168
	global_load_lds_dwordx4 v[222:223], off
	v_lshl_add_u64 v[222:223], s[62:63], 0, v[140:141]
	s_add_i32 m0, s22, 0xe000
	s_nop 0
	global_load_lds_dwordx4 v[222:223], off
	s_waitcnt vmcnt(8)
	s_waitcnt lgkmcnt(0)
	s_barrier
	s_setprio 1
	s_waitcnt lgkmcnt(0)
	v_mfma_f32_16x16x32_bf16 v[126:129], v[146:149], v[178:181], v[126:129]
	v_mfma_f32_16x16x32_bf16 v[126:129], v[150:153], v[182:185], v[126:129]
	v_mfma_f32_16x16x32_bf16 v[118:121], v[154:157], v[178:181], v[118:121]
	v_mfma_f32_16x16x32_bf16 v[118:121], v[158:161], v[182:185], v[118:121]
	v_mfma_f32_16x16x32_bf16 v[110:113], v[146:149], v[186:189], v[110:113]
	v_mfma_f32_16x16x32_bf16 v[110:113], v[150:153], v[190:193], v[110:113]
	v_mfma_f32_16x16x32_bf16 v[102:105], v[154:157], v[186:189], v[102:105]
	v_mfma_f32_16x16x32_bf16 v[102:105], v[158:161], v[190:193], v[102:105]
	v_mfma_f32_16x16x32_bf16 v[92:95], v[146:149], v[194:197], v[92:95]
	v_mfma_f32_16x16x32_bf16 v[92:95], v[150:153], v[200:203], v[92:95]
	v_mfma_f32_16x16x32_bf16 v[84:87], v[154:157], v[194:197], v[84:87]
	v_mfma_f32_16x16x32_bf16 v[84:87], v[158:161], v[200:203], v[84:87]
	v_mfma_f32_16x16x32_bf16 v[76:79], v[146:149], v[206:209], v[76:79]
	v_mfma_f32_16x16x32_bf16 v[76:79], v[150:153], v[210:213], v[76:79]
	v_mfma_f32_16x16x32_bf16 v[68:71], v[154:157], v[206:209], v[68:71]
	v_mfma_f32_16x16x32_bf16 v[68:71], v[158:161], v[210:213], v[68:71]
	s_setprio 0
	s_setprio 1
	v_mfma_f32_16x16x32_bf16 v[122:125], v[162:165], v[178:181], v[122:125]
	v_mfma_f32_16x16x32_bf16 v[122:125], v[166:169], v[182:185], v[122:125]
	v_mfma_f32_16x16x32_bf16 v[114:117], v[170:173], v[178:181], v[114:117]
	v_mfma_f32_16x16x32_bf16 v[114:117], v[174:177], v[182:185], v[114:117]
	v_mfma_f32_16x16x32_bf16 v[106:109], v[162:165], v[186:189], v[106:109]
	v_mfma_f32_16x16x32_bf16 v[106:109], v[166:169], v[190:193], v[106:109]
	v_mfma_f32_16x16x32_bf16 v[98:101], v[170:173], v[186:189], v[98:101]
	v_mfma_f32_16x16x32_bf16 v[98:101], v[174:177], v[190:193], v[98:101]
	v_mfma_f32_16x16x32_bf16 v[88:91], v[162:165], v[194:197], v[88:91]
	v_mfma_f32_16x16x32_bf16 v[88:91], v[166:169], v[200:203], v[88:91]
	v_mfma_f32_16x16x32_bf16 v[80:83], v[170:173], v[194:197], v[80:83]
	v_mfma_f32_16x16x32_bf16 v[80:83], v[174:177], v[200:203], v[80:83]
	v_mfma_f32_16x16x32_bf16 v[72:75], v[162:165], v[206:209], v[72:75]
	v_mfma_f32_16x16x32_bf16 v[72:75], v[166:169], v[210:213], v[72:75]
	v_mfma_f32_16x16x32_bf16 v[64:67], v[170:173], v[206:209], v[64:67]
	v_mfma_f32_16x16x32_bf16 v[64:67], v[174:177], v[210:213], v[64:67]
	s_setprio 0
	s_barrier
	s_add_i32 s28, s30, s21
	v_lshl_add_u64 v[222:223], s[64:65], 0, v[134:135]
	s_mov_b32 m0, s28
	ds_read_b128 v[178:181], v144 offset:16384
	ds_read_b128 v[182:185], v144 offset:17408
	ds_read_b128 v[186:189], v144 offset:18432
	ds_read_b128 v[190:193], v144 offset:19456
	ds_read_b128 v[194:197], v144 offset:20480
	ds_read_b128 v[200:203], v144 offset:21504
	ds_read_b128 v[206:209], v144 offset:22528
	ds_read_b128 v[210:213], v144 offset:23552
	global_load_lds_dwordx4 v[222:223], off
	s_add_i32 m0, s28, 0x2000
	s_add_u32 s28, s64, 0x80000
	v_lshl_add_u64 v[224:225], s[64:65], 0, v[130:131]
	s_addc_u32 s29, s65, 0
	s_add_i32 s30, s31, s21
	global_load_lds_dwordx4 v[224:225], off
	v_lshl_add_u64 v[226:227], s[28:29], 0, v[134:135]
	s_mov_b32 m0, s30
	v_lshl_add_u64 v[228:229], s[66:67], 0, v[132:133]
	global_load_lds_dwordx4 v[226:227], off
	v_lshl_add_u64 v[226:227], s[28:29], 0, v[130:131]
	s_add_i32 m0, s30, 0x2000
	s_nop 0
	global_load_lds_dwordx4 v[226:227], off
	v_lshl_add_u64 v[226:227], s[66:67], 0, v[136:137]
	s_mov_b32 m0, s22
	s_nop 0
	global_load_lds_dwordx4 v[226:227], off
	s_mov_b32 m0, s23
	s_nop 0
	global_load_lds_dwordx4 v[228:229], off
	s_waitcnt vmcnt(8)
	s_waitcnt lgkmcnt(0)
	s_barrier
; #define PG8_STAGE(bufoff, gbase, voff) do { _Pragma("unroll") for (int _i = 0; _i < 2; ++_i) \
;         __builtin_amdgcn_global_load_lds((const unsigned*)((const char*)(gbase) + (voff)[_i]), (PG8_LAS unsigned*)(lds + (bufoff) + ldsw + _i * 8192), 16, 0, 0); } while (0)
; #define PG8_LDA(dst, b, h) do { _Pragma("unroll") for (int m = 0; m < 4; ++m) _Pragma("unroll") for (int k = 0; k < 2; ++k) dst[m][k] = *(const PG8_LAS bf16x8*)(lds + PG8_SA(b, h) + aoff + m * 2048 + k * 1024); } while (0)
; #define PG8_LDB(dst, b, h) do { _Pragma("unroll") for (int n = 0; n < 2; ++n) _Pragma("unroll") for (int k = 0; k < 2; ++k) dst[n][k] = *(const PG8_LAS bf16x8*)(lds + PG8_SB(b, h) + boff + n * 2048 + k * 1024); } while (0)
; #define PG8_MMA(ai, bj, At, Bt) do { __builtin_amdgcn_s_setprio(1); _Pragma("unroll") for (int m = 0; m < 4; ++m) _Pragma("unroll") for (int n = 0; n < 2; ++n) _Pragma("unroll") for (int k = 0; k < 2; ++k) \
;         acc[ai][bj][m][n] = __builtin_amdgcn_mfma_f32_16x16x32_bf16(Bt[n][k], At[m][k], acc[ai][bj][m][n], 0, 0, 0); __builtin_amdgcn_s_setprio(0); } while (0)
; #define PG8_WAIT_V(n) asm volatile("s_waitcnt vmcnt(" #n ")" ::: "memory")
; #define PG8_WAIT_L(n) asm volatile("s_waitcnt lgkmcnt(" #n ")" ::: "memory")
; #define PG8_BAR __builtin_amdgcn_s_barrier()
; #define PG8_SCHED __builtin_amdgcn_sched_barrier(0)
; template <class Epi, class Sched, bool ALIGN_EPI = true, bool SP2 = true>
; __device__ __forceinline__ void gemm_phase(PG8_LAS unsigned char* lds, const Gemm g, const Sched& S, const Epi& E, const int tid) {
;     ...
;             PG8_WAIT_V(8); PG8_WAIT_L(0); PG8_BAR; PG8_MMA(1, 0, At, B0); PG8_MMA(1, 1, At, B1); PG8_BAR; PG8_SCHED;
;             PG8_LDB(B0, 1, 0); PG8_LDB(B1, 1, 1); PG8_SCHED; PG8_LDA(At, 1, 0); PG8_STAGE(PG8_SA(0, 1), a2 + hstepA, voffA);
;             PG8_WAIT_V(8); PG8_WAIT_L(0); PG8_BAR; PG8_MMA(0, 0, At, B0); PG8_MMA(0, 1, At, B1); PG8_BAR; PG8_SCHED;
	s_setprio 1
	s_waitcnt lgkmcnt(0)
	v_mfma_f32_16x16x32_bf16 v[60:63], v[146:149], v[178:181], v[60:63]
	v_mfma_f32_16x16x32_bf16 v[60:63], v[150:153], v[182:185], v[60:63]
	v_mfma_f32_16x16x32_bf16 v[52:55], v[154:157], v[178:181], v[52:55]
	v_mfma_f32_16x16x32_bf16 v[52:55], v[158:161], v[182:185], v[52:55]
	v_mfma_f32_16x16x32_bf16 v[44:47], v[146:149], v[186:189], v[44:47]
	v_mfma_f32_16x16x32_bf16 v[44:47], v[150:153], v[190:193], v[44:47]
	v_mfma_f32_16x16x32_bf16 v[36:39], v[154:157], v[186:189], v[36:39]
	v_mfma_f32_16x16x32_bf16 v[36:39], v[158:161], v[190:193], v[36:39]
	v_mfma_f32_16x16x32_bf16 v[28:31], v[146:149], v[194:197], v[28:31]
	v_mfma_f32_16x16x32_bf16 v[28:31], v[150:153], v[200:203], v[28:31]
	v_mfma_f32_16x16x32_bf16 v[20:23], v[154:157], v[194:197], v[20:23]
	v_mfma_f32_16x16x32_bf16 v[20:23], v[158:161], v[200:203], v[20:23]
	v_mfma_f32_16x16x32_bf16 v[12:15], v[146:149], v[206:209], v[12:15]
	v_mfma_f32_16x16x32_bf16 v[12:15], v[150:153], v[210:213], v[12:15]
	v_mfma_f32_16x16x32_bf16 v[4:7], v[154:157], v[206:209], v[4:7]
	v_mfma_f32_16x16x32_bf16 v[4:7], v[158:161], v[210:213], v[4:7]
	s_setprio 0
	s_setprio 1
	v_mfma_f32_16x16x32_bf16 v[56:59], v[162:165], v[178:181], v[56:59]
	v_mfma_f32_16x16x32_bf16 v[56:59], v[166:169], v[182:185], v[56:59]
	v_mfma_f32_16x16x32_bf16 v[48:51], v[170:173], v[178:181], v[48:51]
	v_mfma_f32_16x16x32_bf16 v[48:51], v[174:177], v[182:185], v[48:51]
	v_mfma_f32_16x16x32_bf16 v[40:43], v[162:165], v[186:189], v[40:43]
	v_mfma_f32_16x16x32_bf16 v[40:43], v[166:169], v[190:193], v[40:43]
	v_mfma_f32_16x16x32_bf16 v[32:35], v[170:173], v[186:189], v[32:35]
	v_mfma_f32_16x16x32_bf16 v[32:35], v[174:177], v[190:193], v[32:35]
	v_mfma_f32_16x16x32_bf16 v[24:27], v[162:165], v[194:197], v[24:27]
	v_mfma_f32_16x16x32_bf16 v[24:27], v[166:169], v[200:203], v[24:27]
	v_mfma_f32_16x16x32_bf16 v[16:19], v[170:173], v[194:197], v[16:19]
	v_mfma_f32_16x16x32_bf16 v[16:19], v[174:177], v[200:203], v[16:19]
	v_mfma_f32_16x16x32_bf16 v[8:11], v[162:165], v[206:209], v[8:11]
	v_mfma_f32_16x16x32_bf16 v[8:11], v[166:169], v[210:213], v[8:11]
	v_mfma_f32_16x16x32_bf16 v[0:3], v[170:173], v[206:209], v[0:3]
	v_mfma_f32_16x16x32_bf16 v[0:3], v[174:177], v[210:213], v[0:3]
	s_setprio 0
	s_barrier
	s_add_i32 s30, 0, 0x18000
	v_add_u32_e32 v145, s30, v142
	s_add_i32 s31, 0, 0x1c000
	ds_read_b128 v[146:149], v145
	ds_read_b128 v[150:153], v145 offset:1024
	ds_read_b128 v[154:157], v145 offset:2048
	ds_read_b128 v[158:161], v145 offset:3072
	v_add_u32_e32 v145, s31, v142
	ds_read_b128 v[162:165], v145
	ds_read_b128 v[166:169], v145 offset:1024
	ds_read_b128 v[170:173], v145 offset:2048
	ds_read_b128 v[174:177], v145 offset:3072
	s_add_u32 s28, s66, 0x80000
	s_addc_u32 s29, s67, 0
	s_mov_b32 m0, s61
	v_lshl_add_u64 v[230:231], s[28:29], 0, v[136:137]
	ds_read_b128 v[178:181], v144 offset:32768
	ds_read_b128 v[182:185], v144 offset:33792
	ds_read_b128 v[186:189], v144 offset:34816
	ds_read_b128 v[190:193], v144 offset:35840
	ds_read_b128 v[194:197], v144 offset:36864
	ds_read_b128 v[200:203], v144 offset:37888
	ds_read_b128 v[206:209], v144 offset:38912
	ds_read_b128 v[210:213], v144 offset:39936
	global_load_lds_dwordx4 v[230:231], off
	v_lshl_add_u64 v[230:231], s[28:29], 0, v[132:133]
	s_mov_b32 m0, s70
	s_nop 0
	global_load_lds_dwordx4 v[230:231], off
	s_waitcnt vmcnt(8)
	s_waitcnt lgkmcnt(0)
	s_barrier
	s_setprio 1
	s_waitcnt lgkmcnt(0)
	v_mfma_f32_16x16x32_bf16 v[126:129], v[146:149], v[178:181], v[126:129]
	v_mfma_f32_16x16x32_bf16 v[126:129], v[150:153], v[182:185], v[126:129]
	v_mfma_f32_16x16x32_bf16 v[118:121], v[154:157], v[178:181], v[118:121]
	v_mfma_f32_16x16x32_bf16 v[118:121], v[158:161], v[182:185], v[118:121]
	v_mfma_f32_16x16x32_bf16 v[110:113], v[146:149], v[186:189], v[110:113]
	v_mfma_f32_16x16x32_bf16 v[110:113], v[150:153], v[190:193], v[110:113]
	v_mfma_f32_16x16x32_bf16 v[102:105], v[154:157], v[186:189], v[102:105]
	v_mfma_f32_16x16x32_bf16 v[102:105], v[158:161], v[190:193], v[102:105]
	v_mfma_f32_16x16x32_bf16 v[92:95], v[146:149], v[194:197], v[92:95]
	v_mfma_f32_16x16x32_bf16 v[92:95], v[150:153], v[200:203], v[92:95]
	v_mfma_f32_16x16x32_bf16 v[84:87], v[154:157], v[194:197], v[84:87]
	v_mfma_f32_16x16x32_bf16 v[84:87], v[158:161], v[200:203], v[84:87]
	v_mfma_f32_16x16x32_bf16 v[76:79], v[146:149], v[206:209], v[76:79]
	v_mfma_f32_16x16x32_bf16 v[76:79], v[150:153], v[210:213], v[76:79]
	v_mfma_f32_16x16x32_bf16 v[68:71], v[154:157], v[206:209], v[68:71]
	v_mfma_f32_16x16x32_bf16 v[68:71], v[158:161], v[210:213], v[68:71]
	s_setprio 0
	s_setprio 1
	v_mfma_f32_16x16x32_bf16 v[122:125], v[162:165], v[178:181], v[122:125]
	v_mfma_f32_16x16x32_bf16 v[122:125], v[166:169], v[182:185], v[122:125]
	v_mfma_f32_16x16x32_bf16 v[114:117], v[170:173], v[178:181], v[114:117]
	v_mfma_f32_16x16x32_bf16 v[114:117], v[174:177], v[182:185], v[114:117]
	v_mfma_f32_16x16x32_bf16 v[106:109], v[162:165], v[186:189], v[106:109]
	v_mfma_f32_16x16x32_bf16 v[106:109], v[166:169], v[190:193], v[106:109]
	v_mfma_f32_16x16x32_bf16 v[98:101], v[170:173], v[186:189], v[98:101]
	v_mfma_f32_16x16x32_bf16 v[98:101], v[174:177], v[190:193], v[98:101]
	v_mfma_f32_16x16x32_bf16 v[88:91], v[162:165], v[194:197], v[88:91]
	v_mfma_f32_16x16x32_bf16 v[88:91], v[166:169], v[200:203], v[88:91]
	v_mfma_f32_16x16x32_bf16 v[80:83], v[170:173], v[194:197], v[80:83]
	v_mfma_f32_16x16x32_bf16 v[80:83], v[174:177], v[200:203], v[80:83]
	v_mfma_f32_16x16x32_bf16 v[72:75], v[162:165], v[206:209], v[72:75]
	v_mfma_f32_16x16x32_bf16 v[72:75], v[166:169], v[210:213], v[72:75]
	v_mfma_f32_16x16x32_bf16 v[64:67], v[170:173], v[206:209], v[64:67]
	v_mfma_f32_16x16x32_bf16 v[64:67], v[174:177], v[210:213], v[64:67]
	s_setprio 0
	s_barrier
; #define PG8_STAGE(bufoff, gbase, voff) do { _Pragma("unroll") for (int _i = 0; _i < 2; ++_i) \
;         __builtin_amdgcn_global_load_lds((const unsigned*)((const char*)(gbase) + (voff)[_i]), (PG8_LAS unsigned*)(lds + (bufoff) + ldsw + _i * 8192), 16, 0, 0); } while (0)
; #define PG8_LDA(dst, b, h) do { _Pragma("unroll") for (int m = 0; m < 4; ++m) _Pragma("unroll") for (int k = 0; k < 2; ++k) dst[m][k] = *(const PG8_LAS bf16x8*)(lds + PG8_SA(b, h) + aoff + m * 2048 + k * 1024); } while (0)
; #define PG8_MMA(ai, bj, At, Bt) do { __builtin_amdgcn_s_setprio(1); _Pragma("unroll") for (int m = 0; m < 4; ++m) _Pragma("unroll") for (int n = 0; n < 2; ++n) _Pragma("unroll") for (int k = 0; k < 2; ++k) \
;         acc[ai][bj][m][n] = __builtin_amdgcn_mfma_f32_16x16x32_bf16(Bt[n][k], At[m][k], acc[ai][bj][m][n], 0, 0, 0); __builtin_amdgcn_s_setprio(0); } while (0)
; #define PG8_WAIT_V(n) asm volatile("s_waitcnt vmcnt(" #n ")" ::: "memory")
; #define PG8_WAIT_L(n) asm volatile("s_waitcnt lgkmcnt(" #n ")" ::: "memory")
; #define PG8_BAR __builtin_amdgcn_s_barrier()
; #define PG8_SCHED __builtin_amdgcn_sched_barrier(0)
; template <class Epi, class Sched, bool ALIGN_EPI = true, bool SP2 = true>
; __device__ __forceinline__ void gemm_phase(PG8_LAS unsigned char* lds, const Gemm g, const Sched& S, const Epi& E, const int tid) {
;     ...
;         for (int t = 0; t < nt; t += 2) {
;             const bool last = (t == nt - 2);
;             const char* a1 = cA + (size_t)(t + 1) * kstep;
;             const char* a2 = last ? nA : cA + (size_t)(t + 2) * kstep; const char* b2 = last ? nB : cB + (size_t)(t + 2) * kstep;
;             const char* a3 = a2 + kstep; const char* b3 = b2 + kstep;
;     ...
;             PG8_LDA(At, 1, 1); PG8_STAGE(PG8_SB(1, 0), b3, voffB); PG8_STAGE(PG8_SB(1, 1), b3 + hstepB, voffB); PG8_STAGE(PG8_SA(1, 0), a3, voffA);
;             PG8_WAIT_V(8); PG8_WAIT_L(0); PG8_BAR; PG8_MMA(1, 0, At, B0); PG8_MMA(1, 1, At, B1); PG8_BAR; PG8_SCHED;
	s_add_i32 s28, s30, s21
	v_lshl_add_u64 v[222:223], v[222:223], 0, s[4:5]
	s_mov_b32 m0, s28
	ds_read_b128 v[178:181], v144 offset:49152
	ds_read_b128 v[182:185], v144 offset:50176
	ds_read_b128 v[186:189], v144 offset:51200
	ds_read_b128 v[190:193], v144 offset:52224
	ds_read_b128 v[194:197], v144 offset:53248
	ds_read_b128 v[200:203], v144 offset:54272
	ds_read_b128 v[206:209], v144 offset:55296
	ds_read_b128 v[210:213], v144 offset:56320
	global_load_lds_dwordx4 v[222:223], off
	s_add_i32 m0, s28, 0x2000
	s_add_u32 s28, s64, 0x80080
	v_lshl_add_u64 v[222:223], v[224:225], 0, s[4:5]
	s_addc_u32 s29, s65, 0
	s_add_i32 s30, s31, s21
	global_load_lds_dwordx4 v[222:223], off
	v_lshl_add_u64 v[222:223], s[28:29], 0, v[134:135]
	s_mov_b32 m0, s30
	s_nop 0
	global_load_lds_dwordx4 v[222:223], off
	v_lshl_add_u64 v[222:223], s[28:29], 0, v[130:131]
	s_add_i32 m0, s30, 0x2000
	s_nop 0
	global_load_lds_dwordx4 v[222:223], off
	v_lshl_add_u64 v[222:223], v[226:227], 0, s[4:5]
	s_mov_b32 m0, s71
	s_nop 0
	global_load_lds_dwordx4 v[222:223], off
	v_lshl_add_u64 v[222:223], v[228:229], 0, s[4:5]
	s_mov_b32 m0, s72
	s_nop 0
	global_load_lds_dwordx4 v[222:223], off
	s_waitcnt vmcnt(8)
	s_waitcnt lgkmcnt(0)
	s_barrier
	s_setprio 1
	s_waitcnt lgkmcnt(0)
	v_mfma_f32_16x16x32_bf16 v[60:63], v[146:149], v[178:181], v[60:63]
	v_mfma_f32_16x16x32_bf16 v[60:63], v[150:153], v[182:185], v[60:63]
	v_mfma_f32_16x16x32_bf16 v[52:55], v[154:157], v[178:181], v[52:55]
	v_mfma_f32_16x16x32_bf16 v[52:55], v[158:161], v[182:185], v[52:55]
	v_mfma_f32_16x16x32_bf16 v[44:47], v[146:149], v[186:189], v[44:47]
	v_mfma_f32_16x16x32_bf16 v[44:47], v[150:153], v[190:193], v[44:47]
	v_mfma_f32_16x16x32_bf16 v[36:39], v[154:157], v[186:189], v[36:39]
	v_mfma_f32_16x16x32_bf16 v[36:39], v[158:161], v[190:193], v[36:39]
	v_mfma_f32_16x16x32_bf16 v[28:31], v[146:149], v[194:197], v[28:31]
	v_mfma_f32_16x16x32_bf16 v[28:31], v[150:153], v[200:203], v[28:31]
	v_mfma_f32_16x16x32_bf16 v[20:23], v[154:157], v[194:197], v[20:23]
	v_mfma_f32_16x16x32_bf16 v[20:23], v[158:161], v[200:203], v[20:23]
	v_mfma_f32_16x16x32_bf16 v[12:15], v[146:149], v[206:209], v[12:15]
	v_mfma_f32_16x16x32_bf16 v[12:15], v[150:153], v[210:213], v[12:15]
	v_mfma_f32_16x16x32_bf16 v[4:7], v[154:157], v[206:209], v[4:7]
	v_mfma_f32_16x16x32_bf16 v[4:7], v[158:161], v[210:213], v[4:7]
	s_setprio 0
	s_setprio 1
	v_mfma_f32_16x16x32_bf16 v[56:59], v[162:165], v[178:181], v[56:59]
	v_mfma_f32_16x16x32_bf16 v[56:59], v[166:169], v[182:185], v[56:59]
	v_mfma_f32_16x16x32_bf16 v[48:51], v[170:173], v[178:181], v[48:51]
	v_mfma_f32_16x16x32_bf16 v[48:51], v[174:177], v[182:185], v[48:51]
	v_mfma_f32_16x16x32_bf16 v[40:43], v[162:165], v[186:189], v[40:43]
	v_mfma_f32_16x16x32_bf16 v[40:43], v[166:169], v[190:193], v[40:43]
	v_mfma_f32_16x16x32_bf16 v[32:35], v[170:173], v[186:189], v[32:35]
	v_mfma_f32_16x16x32_bf16 v[32:35], v[174:177], v[190:193], v[32:35]
	v_mfma_f32_16x16x32_bf16 v[24:27], v[162:165], v[194:197], v[24:27]
	v_mfma_f32_16x16x32_bf16 v[24:27], v[166:169], v[200:203], v[24:27]
	v_mfma_f32_16x16x32_bf16 v[16:19], v[170:173], v[194:197], v[16:19]
	v_mfma_f32_16x16x32_bf16 v[16:19], v[174:177], v[200:203], v[16:19]
	v_mfma_f32_16x16x32_bf16 v[8:11], v[162:165], v[206:209], v[8:11]
	v_mfma_f32_16x16x32_bf16 v[8:11], v[166:169], v[210:213], v[8:11]
	v_mfma_f32_16x16x32_bf16 v[0:3], v[170:173], v[206:209], v[0:3]
	v_mfma_f32_16x16x32_bf16 v[0:3], v[174:177], v[210:213], v[0:3]
	s_setprio 0
	s_barrier
	s_add_i32 s52, s52, 2
	s_add_u32 s62, s62, 0x100
	s_addc_u32 s63, s63, 0
	s_add_u32 s49, s49, 0x100
	s_addc_u32 s51, s51, 0
	s_cmp_gt_u32 s52, 29
	s_cbranch_scc0 .LBB0_1319
	s_and_b64 vcc, exec, s[46:47]
	s_cbranch_vccz .LBB0_1322
	s_barrier
